# P5 (residual+rmsnorm elementwise phase) rewritten by hand: all row loads batched, 2 rows per trip, gains in registers, DPP wave sums, sample rows spread over all workgroups
# speedup vs baseline: 1.1427x; 1.1427x over previous
; __device__ __forceinline__ float bflo(unsigned w) { return __uint_as_float(w << 16); }
; __device__ __forceinline__ float bfhi(unsigned w) { return __uint_as_float(w & 0xffff0000u); }
; __global__ void __launch_bounds__(512, 2) mega_fwd(Args a) {
;     ...
;   if (IN(5)) _Pragma("nounroll") for (int rep_ = 0; rep_ < REPS(5); ++rep_) {
;     const float* g1 = a.in[20]; const float* g2 = a.in[21];
;     for (int m = gw; m < MT; m += NGW) {
;       const float* xrow = m < MP ? x_p + (size_t)m * DM : x_s + (size_t)(m - MP) * DM;
;       f32x4 xin[8];
; #pragma unroll
;       for (int j = 0; j < 8; ++j) xin[j] = *(const f32x4*)(xrow + 4 * (64 * j + lane));
;       f32x4 v[8]; float ss = 0.f;
; #pragma unroll
;       for (int j = 0; j < 8; ++j) {
;         if (m < MP) { const u32x2 w = *(const u32x2*)(MO + (size_t)m * DM + 4 * (64 * j + lane)); v[j] = (f32x4){bflo(w.x), bfhi(w.x), bflo(w.y), bfhi(w.y)}; }
;         else { v[j] = (f32x4){0.f, 0.f, 0.f, 0.f};
; #pragma unroll
;           for (int ks = 0; ks < 16; ++ks) v[j] += *(const f32x4*)(PART + ((size_t)ks * MSAMP + (m - MP)) * DM + 4 * (64 * j + lane)); }
;         ss += (v[j].x * v[j].x + v[j].y * v[j].y) + (v[j].z * v[j].z + v[j].w * v[j].w); }
.LBB0_1111:
	s_cmp_lt_i32 s86, 6
	s_cselect_b64 s[2:3], -1, 0
	s_and_b64 s[0:1], s[2:3], s[0:1]
	s_cmpk_lt_i32 s96, 0x4200
	s_cselect_b64 s[64:65], -1, 0
	s_and_b64 s[2:3], s[0:1], s[64:65]
	s_andn2_b64 vcc, exec, s[2:3]
	v_lshlrev_b32_e32 v170, 4, v195
	s_cbranch_vccnz .LBB0_1150
	s_mov_b64 exec, -1
	v_readlane_b32 s2, v251, 1
	v_readlane_b32 s3, v251, 2
	v_and_b32_e32 v4, 63, v1
	v_lshlrev_b32_e32 v2, 4, v4
	v_add_u32_e32 v3, 0x1000, v2
	v_lshlrev_b32_e32 v4, 3, v4
	v_mov_b32_e32 v177, 0x358637bd
	s_sub_u32 s2, s2, 0xf0
	s_subb_u32 s3, s3, 0
	s_load_dwordx4 s[4:7], s[2:3], 0x0
	s_load_dwordx4 s[20:23], s[2:3], 0xa0
	s_load_dwordx2 s[8:9], s[2:3], 0xd8
	s_load_dwordx2 s[12:13], s[2:3], 0xe0
	s_waitcnt lgkmcnt(0)
	s_add_u32 s14, s12, 0x9900000
	s_addc_u32 s15, s13, 0
	s_add_u32 s16, s12, 0x22600000
	s_addc_u32 s17, s13, 0
	s_add_u32 s12, s12, 0x2ec00000
	s_addc_u32 s13, s13, 0
	s_and_b32 s97, s96, 3
	s_cmp_lg_u32 s97, 0
	s_cbranch_scc1 .Lew5_prompt
	s_lshr_b32 s18, s96, 2
.Lew5_samp_loop:
	s_cmpk_ge_u32 s18, 0x200
	s_cbranch_scc1 .Lew5_prompt
	s_lshl_b32 s97, s18, 13
	s_add_u32 s24, s16, s97
	s_addc_u32 s25, s17, 0
	global_load_dwordx4 v[106:109], v2, s[24:25] offset:0
	global_load_dwordx4 v[110:113], v2, s[24:25] offset:1024
	global_load_dwordx4 v[114:117], v2, s[24:25] offset:2048
	global_load_dwordx4 v[118:121], v2, s[24:25] offset:3072
	global_load_dwordx4 v[122:125], v3, s[24:25] offset:0
	global_load_dwordx4 v[126:129], v3, s[24:25] offset:1024
	global_load_dwordx4 v[130:133], v3, s[24:25] offset:2048
	global_load_dwordx4 v[134:137], v3, s[24:25] offset:3072
	s_add_u32 s24, s24, 0x400000
	s_addc_u32 s25, s25, 0
	global_load_dwordx4 v[10:13], v2, s[24:25] offset:0
	global_load_dwordx4 v[14:17], v2, s[24:25] offset:1024
	global_load_dwordx4 v[18:21], v2, s[24:25] offset:2048
	global_load_dwordx4 v[22:25], v2, s[24:25] offset:3072
	global_load_dwordx4 v[26:29], v3, s[24:25] offset:0
	global_load_dwordx4 v[30:33], v3, s[24:25] offset:1024
	global_load_dwordx4 v[34:37], v3, s[24:25] offset:2048
	global_load_dwordx4 v[38:41], v3, s[24:25] offset:3072
	s_add_u32 s24, s24, 0x400000
	s_addc_u32 s25, s25, 0
	global_load_dwordx4 v[42:45], v2, s[24:25] offset:0
	global_load_dwordx4 v[46:49], v2, s[24:25] offset:1024
	global_load_dwordx4 v[50:53], v2, s[24:25] offset:2048
	global_load_dwordx4 v[54:57], v2, s[24:25] offset:3072
	global_load_dwordx4 v[58:61], v3, s[24:25] offset:0
	global_load_dwordx4 v[62:65], v3, s[24:25] offset:1024
	global_load_dwordx4 v[66:69], v3, s[24:25] offset:2048
	global_load_dwordx4 v[70:73], v3, s[24:25] offset:3072
	s_add_u32 s24, s24, 0x400000
	s_addc_u32 s25, s25, 0
	global_load_dwordx4 v[74:77], v2, s[24:25] offset:0
	global_load_dwordx4 v[78:81], v2, s[24:25] offset:1024
	global_load_dwordx4 v[82:85], v2, s[24:25] offset:2048
	global_load_dwordx4 v[86:89], v2, s[24:25] offset:3072
	global_load_dwordx4 v[90:93], v3, s[24:25] offset:0
	global_load_dwordx4 v[94:97], v3, s[24:25] offset:1024
	global_load_dwordx4 v[98:101], v3, s[24:25] offset:2048
	global_load_dwordx4 v[102:105], v3, s[24:25] offset:3072
	s_add_u32 s24, s24, 0x400000
	s_addc_u32 s25, s25, 0
	s_waitcnt vmcnt(16)
	v_pk_add_f32 v[106:107], v[106:107], v[10:11]
	v_pk_add_f32 v[108:109], v[108:109], v[12:13]
	v_pk_add_f32 v[110:111], v[110:111], v[14:15]
	v_pk_add_f32 v[112:113], v[112:113], v[16:17]
	v_pk_add_f32 v[114:115], v[114:115], v[18:19]
	v_pk_add_f32 v[116:117], v[116:117], v[20:21]
	v_pk_add_f32 v[118:119], v[118:119], v[22:23]
	v_pk_add_f32 v[120:121], v[120:121], v[24:25]
	v_pk_add_f32 v[122:123], v[122:123], v[26:27]
	v_pk_add_f32 v[124:125], v[124:125], v[28:29]
	v_pk_add_f32 v[126:127], v[126:127], v[30:31]
	v_pk_add_f32 v[128:129], v[128:129], v[32:33]
	v_pk_add_f32 v[130:131], v[130:131], v[34:35]
	v_pk_add_f32 v[132:133], v[132:133], v[36:37]
	v_pk_add_f32 v[134:135], v[134:135], v[38:39]
	v_pk_add_f32 v[136:137], v[136:137], v[40:41]
	global_load_dwordx4 v[10:13], v2, s[24:25] offset:0
	global_load_dwordx4 v[14:17], v2, s[24:25] offset:1024
	global_load_dwordx4 v[18:21], v2, s[24:25] offset:2048
	global_load_dwordx4 v[22:25], v2, s[24:25] offset:3072
	global_load_dwordx4 v[26:29], v3, s[24:25] offset:0
	global_load_dwordx4 v[30:33], v3, s[24:25] offset:1024
	global_load_dwordx4 v[34:37], v3, s[24:25] offset:2048
	global_load_dwordx4 v[38:41], v3, s[24:25] offset:3072
	s_add_u32 s24, s24, 0x400000
	s_addc_u32 s25, s25, 0
	s_waitcnt vmcnt(16)
	v_pk_add_f32 v[106:107], v[106:107], v[42:43]
	v_pk_add_f32 v[108:109], v[108:109], v[44:45]
	v_pk_add_f32 v[110:111], v[110:111], v[46:47]
	v_pk_add_f32 v[112:113], v[112:113], v[48:49]
	v_pk_add_f32 v[114:115], v[114:115], v[50:51]
	v_pk_add_f32 v[116:117], v[116:117], v[52:53]
	v_pk_add_f32 v[118:119], v[118:119], v[54:55]
	v_pk_add_f32 v[120:121], v[120:121], v[56:57]
	v_pk_add_f32 v[122:123], v[122:123], v[58:59]
	v_pk_add_f32 v[124:125], v[124:125], v[60:61]
	v_pk_add_f32 v[126:127], v[126:127], v[62:63]
	v_pk_add_f32 v[128:129], v[128:129], v[64:65]
	v_pk_add_f32 v[130:131], v[130:131], v[66:67]
	v_pk_add_f32 v[132:133], v[132:133], v[68:69]
	v_pk_add_f32 v[134:135], v[134:135], v[70:71]
	v_pk_add_f32 v[136:137], v[136:137], v[72:73]
	global_load_dwordx4 v[42:45], v2, s[24:25] offset:0
	global_load_dwordx4 v[46:49], v2, s[24:25] offset:1024
	global_load_dwordx4 v[50:53], v2, s[24:25] offset:2048
	global_load_dwordx4 v[54:57], v2, s[24:25] offset:3072
	global_load_dwordx4 v[58:61], v3, s[24:25] offset:0
	global_load_dwordx4 v[62:65], v3, s[24:25] offset:1024
	global_load_dwordx4 v[66:69], v3, s[24:25] offset:2048
	global_load_dwordx4 v[70:73], v3, s[24:25] offset:3072
	s_add_u32 s24, s24, 0x400000
	s_addc_u32 s25, s25, 0
	s_waitcnt vmcnt(16)
; __global__ void __launch_bounds__(512, 2) mega_fwd(Args a) {
;     ...
;         else { v[j] = (f32x4){0.f, 0.f, 0.f, 0.f};
; #pragma unroll
;           for (int ks = 0; ks < 16; ++ks) v[j] += *(const f32x4*)(PART + ((size_t)ks * MSAMP + (m - MP)) * DM + 4 * (64 * j + lane)); }
;         ss += (v[j].x * v[j].x + v[j].y * v[j].y) + (v[j].z * v[j].z + v[j].w * v[j].w); }
	v_pk_add_f32 v[106:107], v[106:107], v[74:75]
	v_pk_add_f32 v[108:109], v[108:109], v[76:77]
	v_pk_add_f32 v[110:111], v[110:111], v[78:79]
	v_pk_add_f32 v[112:113], v[112:113], v[80:81]
	v_pk_add_f32 v[114:115], v[114:115], v[82:83]
	v_pk_add_f32 v[116:117], v[116:117], v[84:85]
	v_pk_add_f32 v[118:119], v[118:119], v[86:87]
	v_pk_add_f32 v[120:121], v[120:121], v[88:89]
	v_pk_add_f32 v[122:123], v[122:123], v[90:91]
	v_pk_add_f32 v[124:125], v[124:125], v[92:93]
	v_pk_add_f32 v[126:127], v[126:127], v[94:95]
	v_pk_add_f32 v[128:129], v[128:129], v[96:97]
	v_pk_add_f32 v[130:131], v[130:131], v[98:99]
	v_pk_add_f32 v[132:133], v[132:133], v[100:101]
	v_pk_add_f32 v[134:135], v[134:135], v[102:103]
	v_pk_add_f32 v[136:137], v[136:137], v[104:105]
	global_load_dwordx4 v[74:77], v2, s[24:25] offset:0
	global_load_dwordx4 v[78:81], v2, s[24:25] offset:1024
	global_load_dwordx4 v[82:85], v2, s[24:25] offset:2048
	global_load_dwordx4 v[86:89], v2, s[24:25] offset:3072
	global_load_dwordx4 v[90:93], v3, s[24:25] offset:0
	global_load_dwordx4 v[94:97], v3, s[24:25] offset:1024
	global_load_dwordx4 v[98:101], v3, s[24:25] offset:2048
	global_load_dwordx4 v[102:105], v3, s[24:25] offset:3072
	s_add_u32 s24, s24, 0x400000
	s_addc_u32 s25, s25, 0
	s_waitcnt vmcnt(16)
	v_pk_add_f32 v[106:107], v[106:107], v[10:11]
	v_pk_add_f32 v[108:109], v[108:109], v[12:13]
	v_pk_add_f32 v[110:111], v[110:111], v[14:15]
	v_pk_add_f32 v[112:113], v[112:113], v[16:17]
	v_pk_add_f32 v[114:115], v[114:115], v[18:19]
	v_pk_add_f32 v[116:117], v[116:117], v[20:21]
	v_pk_add_f32 v[118:119], v[118:119], v[22:23]
	v_pk_add_f32 v[120:121], v[120:121], v[24:25]
	v_pk_add_f32 v[122:123], v[122:123], v[26:27]
	v_pk_add_f32 v[124:125], v[124:125], v[28:29]
	v_pk_add_f32 v[126:127], v[126:127], v[30:31]
	v_pk_add_f32 v[128:129], v[128:129], v[32:33]
	v_pk_add_f32 v[130:131], v[130:131], v[34:35]
	v_pk_add_f32 v[132:133], v[132:133], v[36:37]
	v_pk_add_f32 v[134:135], v[134:135], v[38:39]
	v_pk_add_f32 v[136:137], v[136:137], v[40:41]
	global_load_dwordx4 v[10:13], v2, s[24:25] offset:0
	global_load_dwordx4 v[14:17], v2, s[24:25] offset:1024
	global_load_dwordx4 v[18:21], v2, s[24:25] offset:2048
	global_load_dwordx4 v[22:25], v2, s[24:25] offset:3072
	global_load_dwordx4 v[26:29], v3, s[24:25] offset:0
	global_load_dwordx4 v[30:33], v3, s[24:25] offset:1024
	global_load_dwordx4 v[34:37], v3, s[24:25] offset:2048
	global_load_dwordx4 v[38:41], v3, s[24:25] offset:3072
	s_add_u32 s24, s24, 0x400000
	s_addc_u32 s25, s25, 0
	s_waitcnt vmcnt(16)
	v_pk_add_f32 v[106:107], v[106:107], v[42:43]
	v_pk_add_f32 v[108:109], v[108:109], v[44:45]
	v_pk_add_f32 v[110:111], v[110:111], v[46:47]
	v_pk_add_f32 v[112:113], v[112:113], v[48:49]
	v_pk_add_f32 v[114:115], v[114:115], v[50:51]
	v_pk_add_f32 v[116:117], v[116:117], v[52:53]
	v_pk_add_f32 v[118:119], v[118:119], v[54:55]
	v_pk_add_f32 v[120:121], v[120:121], v[56:57]
	v_pk_add_f32 v[122:123], v[122:123], v[58:59]
	v_pk_add_f32 v[124:125], v[124:125], v[60:61]
	v_pk_add_f32 v[126:127], v[126:127], v[62:63]
	v_pk_add_f32 v[128:129], v[128:129], v[64:65]
	v_pk_add_f32 v[130:131], v[130:131], v[66:67]
	v_pk_add_f32 v[132:133], v[132:133], v[68:69]
	v_pk_add_f32 v[134:135], v[134:135], v[70:71]
	v_pk_add_f32 v[136:137], v[136:137], v[72:73]
	global_load_dwordx4 v[42:45], v2, s[24:25] offset:0
	global_load_dwordx4 v[46:49], v2, s[24:25] offset:1024
	global_load_dwordx4 v[50:53], v2, s[24:25] offset:2048
	global_load_dwordx4 v[54:57], v2, s[24:25] offset:3072
	global_load_dwordx4 v[58:61], v3, s[24:25] offset:0
	global_load_dwordx4 v[62:65], v3, s[24:25] offset:1024
	global_load_dwordx4 v[66:69], v3, s[24:25] offset:2048
	global_load_dwordx4 v[70:73], v3, s[24:25] offset:3072
	s_add_u32 s24, s24, 0x400000
	s_addc_u32 s25, s25, 0
	s_waitcnt vmcnt(16)
	v_pk_add_f32 v[106:107], v[106:107], v[74:75]
	v_pk_add_f32 v[108:109], v[108:109], v[76:77]
	v_pk_add_f32 v[110:111], v[110:111], v[78:79]
	v_pk_add_f32 v[112:113], v[112:113], v[80:81]
	v_pk_add_f32 v[114:115], v[114:115], v[82:83]
	v_pk_add_f32 v[116:117], v[116:117], v[84:85]
	v_pk_add_f32 v[118:119], v[118:119], v[86:87]
	v_pk_add_f32 v[120:121], v[120:121], v[88:89]
	v_pk_add_f32 v[122:123], v[122:123], v[90:91]
	v_pk_add_f32 v[124:125], v[124:125], v[92:93]
	v_pk_add_f32 v[126:127], v[126:127], v[94:95]
	v_pk_add_f32 v[128:129], v[128:129], v[96:97]
	v_pk_add_f32 v[130:131], v[130:131], v[98:99]
	v_pk_add_f32 v[132:133], v[132:133], v[100:101]
	v_pk_add_f32 v[134:135], v[134:135], v[102:103]
	v_pk_add_f32 v[136:137], v[136:137], v[104:105]
	global_load_dwordx4 v[74:77], v2, s[24:25] offset:0
	global_load_dwordx4 v[78:81], v2, s[24:25] offset:1024
	global_load_dwordx4 v[82:85], v2, s[24:25] offset:2048
	global_load_dwordx4 v[86:89], v2, s[24:25] offset:3072
	global_load_dwordx4 v[90:93], v3, s[24:25] offset:0
	global_load_dwordx4 v[94:97], v3, s[24:25] offset:1024
	global_load_dwordx4 v[98:101], v3, s[24:25] offset:2048
	global_load_dwordx4 v[102:105], v3, s[24:25] offset:3072
	s_add_u32 s24, s24, 0x400000
	s_addc_u32 s25, s25, 0
	s_waitcnt vmcnt(16)
; __global__ void __launch_bounds__(512, 2) mega_fwd(Args a) {
;     ...
;         else { v[j] = (f32x4){0.f, 0.f, 0.f, 0.f};
; #pragma unroll
;           for (int ks = 0; ks < 16; ++ks) v[j] += *(const f32x4*)(PART + ((size_t)ks * MSAMP + (m - MP)) * DM + 4 * (64 * j + lane)); }
;         ss += (v[j].x * v[j].x + v[j].y * v[j].y) + (v[j].z * v[j].z + v[j].w * v[j].w); }
	v_pk_add_f32 v[106:107], v[106:107], v[10:11]
	v_pk_add_f32 v[108:109], v[108:109], v[12:13]
	v_pk_add_f32 v[110:111], v[110:111], v[14:15]
	v_pk_add_f32 v[112:113], v[112:113], v[16:17]
	v_pk_add_f32 v[114:115], v[114:115], v[18:19]
	v_pk_add_f32 v[116:117], v[116:117], v[20:21]
	v_pk_add_f32 v[118:119], v[118:119], v[22:23]
	v_pk_add_f32 v[120:121], v[120:121], v[24:25]
	v_pk_add_f32 v[122:123], v[122:123], v[26:27]
	v_pk_add_f32 v[124:125], v[124:125], v[28:29]
	v_pk_add_f32 v[126:127], v[126:127], v[30:31]
	v_pk_add_f32 v[128:129], v[128:129], v[32:33]
	v_pk_add_f32 v[130:131], v[130:131], v[34:35]
	v_pk_add_f32 v[132:133], v[132:133], v[36:37]
	v_pk_add_f32 v[134:135], v[134:135], v[38:39]
	v_pk_add_f32 v[136:137], v[136:137], v[40:41]
	global_load_dwordx4 v[10:13], v2, s[24:25] offset:0
	global_load_dwordx4 v[14:17], v2, s[24:25] offset:1024
	global_load_dwordx4 v[18:21], v2, s[24:25] offset:2048
	global_load_dwordx4 v[22:25], v2, s[24:25] offset:3072
	global_load_dwordx4 v[26:29], v3, s[24:25] offset:0
	global_load_dwordx4 v[30:33], v3, s[24:25] offset:1024
	global_load_dwordx4 v[34:37], v3, s[24:25] offset:2048
	global_load_dwordx4 v[38:41], v3, s[24:25] offset:3072
	s_add_u32 s24, s24, 0x400000
	s_addc_u32 s25, s25, 0
	s_waitcnt vmcnt(16)
	v_pk_add_f32 v[106:107], v[106:107], v[42:43]
	v_pk_add_f32 v[108:109], v[108:109], v[44:45]
	v_pk_add_f32 v[110:111], v[110:111], v[46:47]
	v_pk_add_f32 v[112:113], v[112:113], v[48:49]
	v_pk_add_f32 v[114:115], v[114:115], v[50:51]
	v_pk_add_f32 v[116:117], v[116:117], v[52:53]
	v_pk_add_f32 v[118:119], v[118:119], v[54:55]
	v_pk_add_f32 v[120:121], v[120:121], v[56:57]
	v_pk_add_f32 v[122:123], v[122:123], v[58:59]
	v_pk_add_f32 v[124:125], v[124:125], v[60:61]
	v_pk_add_f32 v[126:127], v[126:127], v[62:63]
	v_pk_add_f32 v[128:129], v[128:129], v[64:65]
	v_pk_add_f32 v[130:131], v[130:131], v[66:67]
	v_pk_add_f32 v[132:133], v[132:133], v[68:69]
	v_pk_add_f32 v[134:135], v[134:135], v[70:71]
	v_pk_add_f32 v[136:137], v[136:137], v[72:73]
	global_load_dwordx4 v[42:45], v2, s[24:25] offset:0
	global_load_dwordx4 v[46:49], v2, s[24:25] offset:1024
	global_load_dwordx4 v[50:53], v2, s[24:25] offset:2048
	global_load_dwordx4 v[54:57], v2, s[24:25] offset:3072
	global_load_dwordx4 v[58:61], v3, s[24:25] offset:0
	global_load_dwordx4 v[62:65], v3, s[24:25] offset:1024
	global_load_dwordx4 v[66:69], v3, s[24:25] offset:2048
	global_load_dwordx4 v[70:73], v3, s[24:25] offset:3072
	s_add_u32 s24, s24, 0x400000
	s_addc_u32 s25, s25, 0
	s_waitcnt vmcnt(16)
	v_pk_add_f32 v[106:107], v[106:107], v[74:75]
	v_pk_add_f32 v[108:109], v[108:109], v[76:77]
	v_pk_add_f32 v[110:111], v[110:111], v[78:79]
	v_pk_add_f32 v[112:113], v[112:113], v[80:81]
	v_pk_add_f32 v[114:115], v[114:115], v[82:83]
	v_pk_add_f32 v[116:117], v[116:117], v[84:85]
	v_pk_add_f32 v[118:119], v[118:119], v[86:87]
	v_pk_add_f32 v[120:121], v[120:121], v[88:89]
	v_pk_add_f32 v[122:123], v[122:123], v[90:91]
	v_pk_add_f32 v[124:125], v[124:125], v[92:93]
	v_pk_add_f32 v[126:127], v[126:127], v[94:95]
	v_pk_add_f32 v[128:129], v[128:129], v[96:97]
	v_pk_add_f32 v[130:131], v[130:131], v[98:99]
	v_pk_add_f32 v[132:133], v[132:133], v[100:101]
	v_pk_add_f32 v[134:135], v[134:135], v[102:103]
	v_pk_add_f32 v[136:137], v[136:137], v[104:105]
	global_load_dwordx4 v[74:77], v2, s[24:25] offset:0
	global_load_dwordx4 v[78:81], v2, s[24:25] offset:1024
	global_load_dwordx4 v[82:85], v2, s[24:25] offset:2048
	global_load_dwordx4 v[86:89], v2, s[24:25] offset:3072
	global_load_dwordx4 v[90:93], v3, s[24:25] offset:0
	global_load_dwordx4 v[94:97], v3, s[24:25] offset:1024
	global_load_dwordx4 v[98:101], v3, s[24:25] offset:2048
	global_load_dwordx4 v[102:105], v3, s[24:25] offset:3072
	s_add_u32 s24, s24, 0x400000
	s_addc_u32 s25, s25, 0
	s_waitcnt vmcnt(16)
	v_pk_add_f32 v[106:107], v[106:107], v[10:11]
	v_pk_add_f32 v[108:109], v[108:109], v[12:13]
	v_pk_add_f32 v[110:111], v[110:111], v[14:15]
	v_pk_add_f32 v[112:113], v[112:113], v[16:17]
	v_pk_add_f32 v[114:115], v[114:115], v[18:19]
	v_pk_add_f32 v[116:117], v[116:117], v[20:21]
	v_pk_add_f32 v[118:119], v[118:119], v[22:23]
	v_pk_add_f32 v[120:121], v[120:121], v[24:25]
	v_pk_add_f32 v[122:123], v[122:123], v[26:27]
	v_pk_add_f32 v[124:125], v[124:125], v[28:29]
	v_pk_add_f32 v[126:127], v[126:127], v[30:31]
	v_pk_add_f32 v[128:129], v[128:129], v[32:33]
	v_pk_add_f32 v[130:131], v[130:131], v[34:35]
	v_pk_add_f32 v[132:133], v[132:133], v[36:37]
	v_pk_add_f32 v[134:135], v[134:135], v[38:39]
	v_pk_add_f32 v[136:137], v[136:137], v[40:41]
	global_load_dwordx4 v[10:13], v2, s[24:25] offset:0
	global_load_dwordx4 v[14:17], v2, s[24:25] offset:1024
	global_load_dwordx4 v[18:21], v2, s[24:25] offset:2048
	global_load_dwordx4 v[22:25], v2, s[24:25] offset:3072
	global_load_dwordx4 v[26:29], v3, s[24:25] offset:0
	global_load_dwordx4 v[30:33], v3, s[24:25] offset:1024
	global_load_dwordx4 v[34:37], v3, s[24:25] offset:2048
	global_load_dwordx4 v[38:41], v3, s[24:25] offset:3072
	s_add_u32 s24, s24, 0x400000
	s_addc_u32 s25, s25, 0
	s_waitcnt vmcnt(16)
; __device__ __forceinline__ float bflo(unsigned w) { return __uint_as_float(w << 16); }
; __device__ __forceinline__ float bfhi(unsigned w) { return __uint_as_float(w & 0xffff0000u); }
; __global__ void __launch_bounds__(512, 2) mega_fwd(Args a) {
;     ...
;       for (int j = 0; j < 8; ++j) xin[j] = *(const f32x4*)(xrow + 4 * (64 * j + lane));
;       f32x4 v[8]; float ss = 0.f;
; #pragma unroll
;       for (int j = 0; j < 8; ++j) {
;         if (m < MP) { const u32x2 w = *(const u32x2*)(MO + (size_t)m * DM + 4 * (64 * j + lane)); v[j] = (f32x4){bflo(w.x), bfhi(w.x), bflo(w.y), bfhi(w.y)}; }
;         else { v[j] = (f32x4){0.f, 0.f, 0.f, 0.f};
; #pragma unroll
;           for (int ks = 0; ks < 16; ++ks) v[j] += *(const f32x4*)(PART + ((size_t)ks * MSAMP + (m - MP)) * DM + 4 * (64 * j + lane)); }
;         ss += (v[j].x * v[j].x + v[j].y * v[j].y) + (v[j].z * v[j].z + v[j].w * v[j].w); }
;       const float r = rsqrtf(wave_sum(ss) * (1.f / DM) + EPS); float ss2 = 0.f;
; #pragma unroll
;       for (int j = 0; j < 8; ++j) { const f32x4 gn = *(const f32x4*)(g1 + 4 * (64 * j + lane)); const f32x4 xv = xin[j];
	v_pk_add_f32 v[106:107], v[106:107], v[42:43]
	v_pk_add_f32 v[108:109], v[108:109], v[44:45]
	v_pk_add_f32 v[110:111], v[110:111], v[46:47]
	v_pk_add_f32 v[112:113], v[112:113], v[48:49]
	v_pk_add_f32 v[114:115], v[114:115], v[50:51]
	v_pk_add_f32 v[116:117], v[116:117], v[52:53]
	v_pk_add_f32 v[118:119], v[118:119], v[54:55]
	v_pk_add_f32 v[120:121], v[120:121], v[56:57]
	v_pk_add_f32 v[122:123], v[122:123], v[58:59]
	v_pk_add_f32 v[124:125], v[124:125], v[60:61]
	v_pk_add_f32 v[126:127], v[126:127], v[62:63]
	v_pk_add_f32 v[128:129], v[128:129], v[64:65]
	v_pk_add_f32 v[130:131], v[130:131], v[66:67]
	v_pk_add_f32 v[132:133], v[132:133], v[68:69]
	v_pk_add_f32 v[134:135], v[134:135], v[70:71]
	v_pk_add_f32 v[136:137], v[136:137], v[72:73]
	global_load_dwordx4 v[42:45], v2, s[24:25] offset:0
	global_load_dwordx4 v[46:49], v2, s[24:25] offset:1024
	global_load_dwordx4 v[50:53], v2, s[24:25] offset:2048
	global_load_dwordx4 v[54:57], v2, s[24:25] offset:3072
	global_load_dwordx4 v[58:61], v3, s[24:25] offset:0
	global_load_dwordx4 v[62:65], v3, s[24:25] offset:1024
	global_load_dwordx4 v[66:69], v3, s[24:25] offset:2048
	global_load_dwordx4 v[70:73], v3, s[24:25] offset:3072
	s_add_u32 s24, s24, 0x400000
	s_addc_u32 s25, s25, 0
	s_waitcnt vmcnt(16)
	v_pk_add_f32 v[106:107], v[106:107], v[74:75]
	v_pk_add_f32 v[108:109], v[108:109], v[76:77]
	v_pk_add_f32 v[110:111], v[110:111], v[78:79]
	v_pk_add_f32 v[112:113], v[112:113], v[80:81]
	v_pk_add_f32 v[114:115], v[114:115], v[82:83]
	v_pk_add_f32 v[116:117], v[116:117], v[84:85]
	v_pk_add_f32 v[118:119], v[118:119], v[86:87]
	v_pk_add_f32 v[120:121], v[120:121], v[88:89]
	v_pk_add_f32 v[122:123], v[122:123], v[90:91]
	v_pk_add_f32 v[124:125], v[124:125], v[92:93]
	v_pk_add_f32 v[126:127], v[126:127], v[94:95]
	v_pk_add_f32 v[128:129], v[128:129], v[96:97]
	v_pk_add_f32 v[130:131], v[130:131], v[98:99]
	v_pk_add_f32 v[132:133], v[132:133], v[100:101]
	v_pk_add_f32 v[134:135], v[134:135], v[102:103]
	v_pk_add_f32 v[136:137], v[136:137], v[104:105]
	global_load_dwordx4 v[74:77], v2, s[24:25] offset:0
	global_load_dwordx4 v[78:81], v2, s[24:25] offset:1024
	global_load_dwordx4 v[82:85], v2, s[24:25] offset:2048
	global_load_dwordx4 v[86:89], v2, s[24:25] offset:3072
	global_load_dwordx4 v[90:93], v3, s[24:25] offset:0
	global_load_dwordx4 v[94:97], v3, s[24:25] offset:1024
	global_load_dwordx4 v[98:101], v3, s[24:25] offset:2048
	global_load_dwordx4 v[102:105], v3, s[24:25] offset:3072
	s_waitcnt vmcnt(16)
	v_pk_add_f32 v[106:107], v[106:107], v[10:11]
	v_pk_add_f32 v[108:109], v[108:109], v[12:13]
	v_pk_add_f32 v[110:111], v[110:111], v[14:15]
	v_pk_add_f32 v[112:113], v[112:113], v[16:17]
	v_pk_add_f32 v[114:115], v[114:115], v[18:19]
	v_pk_add_f32 v[116:117], v[116:117], v[20:21]
	v_pk_add_f32 v[118:119], v[118:119], v[22:23]
	v_pk_add_f32 v[120:121], v[120:121], v[24:25]
	v_pk_add_f32 v[122:123], v[122:123], v[26:27]
	v_pk_add_f32 v[124:125], v[124:125], v[28:29]
	v_pk_add_f32 v[126:127], v[126:127], v[30:31]
	v_pk_add_f32 v[128:129], v[128:129], v[32:33]
	v_pk_add_f32 v[130:131], v[130:131], v[34:35]
	v_pk_add_f32 v[132:133], v[132:133], v[36:37]
	v_pk_add_f32 v[134:135], v[134:135], v[38:39]
	v_pk_add_f32 v[136:137], v[136:137], v[40:41]
	s_waitcnt vmcnt(8)
	v_pk_add_f32 v[106:107], v[106:107], v[42:43]
	v_pk_add_f32 v[108:109], v[108:109], v[44:45]
	v_pk_add_f32 v[110:111], v[110:111], v[46:47]
	v_pk_add_f32 v[112:113], v[112:113], v[48:49]
	v_pk_add_f32 v[114:115], v[114:115], v[50:51]
	v_pk_add_f32 v[116:117], v[116:117], v[52:53]
	v_pk_add_f32 v[118:119], v[118:119], v[54:55]
	v_pk_add_f32 v[120:121], v[120:121], v[56:57]
	v_pk_add_f32 v[122:123], v[122:123], v[58:59]
	v_pk_add_f32 v[124:125], v[124:125], v[60:61]
	v_pk_add_f32 v[126:127], v[126:127], v[62:63]
	v_pk_add_f32 v[128:129], v[128:129], v[64:65]
	v_pk_add_f32 v[130:131], v[130:131], v[66:67]
	v_pk_add_f32 v[132:133], v[132:133], v[68:69]
	v_pk_add_f32 v[134:135], v[134:135], v[70:71]
	v_pk_add_f32 v[136:137], v[136:137], v[72:73]
	s_waitcnt vmcnt(0)
	v_pk_add_f32 v[106:107], v[106:107], v[74:75]
	v_pk_add_f32 v[108:109], v[108:109], v[76:77]
	v_pk_add_f32 v[110:111], v[110:111], v[78:79]
	v_pk_add_f32 v[112:113], v[112:113], v[80:81]
	v_pk_add_f32 v[114:115], v[114:115], v[82:83]
	v_pk_add_f32 v[116:117], v[116:117], v[84:85]
	v_pk_add_f32 v[118:119], v[118:119], v[86:87]
	v_pk_add_f32 v[120:121], v[120:121], v[88:89]
	v_pk_add_f32 v[122:123], v[122:123], v[90:91]
	v_pk_add_f32 v[124:125], v[124:125], v[92:93]
	v_pk_add_f32 v[126:127], v[126:127], v[94:95]
	v_pk_add_f32 v[128:129], v[128:129], v[96:97]
	v_pk_add_f32 v[130:131], v[130:131], v[98:99]
	v_pk_add_f32 v[132:133], v[132:133], v[100:101]
	v_pk_add_f32 v[134:135], v[134:135], v[102:103]
	v_pk_add_f32 v[136:137], v[136:137], v[104:105]
	s_lshl_b32 s97, s18, 13
	s_add_u32 s26, s6, s97
	s_addc_u32 s27, s7, 0
	global_load_dwordx4 v[74:77], v2, s[26:27] offset:0
	global_load_dwordx4 v[78:81], v2, s[26:27] offset:1024
	global_load_dwordx4 v[82:85], v2, s[26:27] offset:2048
	global_load_dwordx4 v[86:89], v2, s[26:27] offset:3072
	global_load_dwordx4 v[90:93], v3, s[26:27] offset:0
	global_load_dwordx4 v[94:97], v3, s[26:27] offset:1024
	global_load_dwordx4 v[98:101], v3, s[26:27] offset:2048
	global_load_dwordx4 v[102:105], v3, s[26:27] offset:3072
	global_load_dwordx4 v[10:13], v2, s[20:21] offset:0
	global_load_dwordx4 v[14:17], v2, s[20:21] offset:1024
	global_load_dwordx4 v[18:21], v2, s[20:21] offset:2048
	global_load_dwordx4 v[22:25], v2, s[20:21] offset:3072
	global_load_dwordx4 v[26:29], v3, s[20:21] offset:0
	global_load_dwordx4 v[30:33], v3, s[20:21] offset:1024
	global_load_dwordx4 v[34:37], v3, s[20:21] offset:2048
	global_load_dwordx4 v[38:41], v3, s[20:21] offset:3072
	global_load_dwordx4 v[42:45], v2, s[22:23] offset:0
	global_load_dwordx4 v[46:49], v2, s[22:23] offset:1024
	global_load_dwordx4 v[50:53], v2, s[22:23] offset:2048
	global_load_dwordx4 v[54:57], v2, s[22:23] offset:3072
	global_load_dwordx4 v[58:61], v3, s[22:23] offset:0
	global_load_dwordx4 v[62:65], v3, s[22:23] offset:1024
	global_load_dwordx4 v[66:69], v3, s[22:23] offset:2048
	global_load_dwordx4 v[70:73], v3, s[22:23] offset:3072
	s_waitcnt vmcnt(0)
; __global__ void __launch_bounds__(512, 2) mega_fwd(Args a) {
;     ...
;         ss += (v[j].x * v[j].x + v[j].y * v[j].y) + (v[j].z * v[j].z + v[j].w * v[j].w); }
;       const float r = rsqrtf(wave_sum(ss) * (1.f / DM) + EPS); float ss2 = 0.f;
; #pragma unroll
;       for (int j = 0; j < 8; ++j) { const f32x4 gn = *(const f32x4*)(g1 + 4 * (64 * j + lane)); const f32x4 xv = xin[j];
;         v[j] = xv + v[j] * r * gn; *(f32x4*)(out + O_Y + (size_t)m * DM + 4 * (64 * j + lane)) = v[j];
;         ss2 += (v[j].x * v[j].x + v[j].y * v[j].y) + (v[j].z * v[j].z + v[j].w * v[j].w); }
;       const float r2 = rsqrtf(wave_sum(ss2) * (1.f / DM) + EPS);
; #pragma unroll
;       for (int j = 0; j < 8; ++j) { const f32x4 gn = *(const f32x4*)(g2 + 4 * (64 * j + lane)); const f32x4 y = v[j] * r2 * gn;
	v_mov_b32_e32 v9, 0
	v_mul_f32_e32 v174, v106, v106
	v_fmac_f32_e32 v174, v107, v107
	v_mul_f32_e32 v175, v108, v108
	v_fmac_f32_e32 v175, v109, v109
	v_add_f32_e32 v174, v174, v175
	v_add_f32_e32 v9, v9, v174
	v_mul_f32_e32 v174, v110, v110
	v_fmac_f32_e32 v174, v111, v111
	v_mul_f32_e32 v175, v112, v112
	v_fmac_f32_e32 v175, v113, v113
	v_add_f32_e32 v174, v174, v175
	v_add_f32_e32 v9, v9, v174
	v_mul_f32_e32 v174, v114, v114
	v_fmac_f32_e32 v174, v115, v115
	v_mul_f32_e32 v175, v116, v116
	v_fmac_f32_e32 v175, v117, v117
	v_add_f32_e32 v174, v174, v175
	v_add_f32_e32 v9, v9, v174
	v_mul_f32_e32 v174, v118, v118
	v_fmac_f32_e32 v174, v119, v119
	v_mul_f32_e32 v175, v120, v120
	v_fmac_f32_e32 v175, v121, v121
	v_add_f32_e32 v174, v174, v175
	v_add_f32_e32 v9, v9, v174
	v_mul_f32_e32 v174, v122, v122
	v_fmac_f32_e32 v174, v123, v123
	v_mul_f32_e32 v175, v124, v124
	v_fmac_f32_e32 v175, v125, v125
	v_add_f32_e32 v174, v174, v175
	v_add_f32_e32 v9, v9, v174
	v_mul_f32_e32 v174, v126, v126
	v_fmac_f32_e32 v174, v127, v127
	v_mul_f32_e32 v175, v128, v128
	v_fmac_f32_e32 v175, v129, v129
	v_add_f32_e32 v174, v174, v175
	v_add_f32_e32 v9, v9, v174
	v_mul_f32_e32 v174, v130, v130
	v_fmac_f32_e32 v174, v131, v131
	v_mul_f32_e32 v175, v132, v132
	v_fmac_f32_e32 v175, v133, v133
	v_add_f32_e32 v174, v174, v175
	v_add_f32_e32 v9, v9, v174
	v_mul_f32_e32 v174, v134, v134
	v_fmac_f32_e32 v174, v135, v135
	v_mul_f32_e32 v175, v136, v136
	v_fmac_f32_e32 v175, v137, v137
	v_add_f32_e32 v174, v174, v175
	v_add_f32_e32 v9, v9, v174
	s_nop 1
	v_add_f32_dpp v9, v9, v9 quad_perm:[1,0,3,2] row_mask:0xf bank_mask:0xf
	s_nop 1
	v_add_f32_dpp v9, v9, v9 quad_perm:[2,3,0,1] row_mask:0xf bank_mask:0xf
	s_nop 1
	v_add_f32_dpp v9, v9, v9 row_half_mirror row_mask:0xf bank_mask:0xf
	s_nop 1
	v_add_f32_dpp v9, v9, v9 row_mirror row_mask:0xf bank_mask:0xf
	s_nop 1
	v_add_f32_dpp v9, v9, v9 row_bcast:15 row_mask:0xa bank_mask:0xf
	s_nop 1
	v_add_f32_dpp v9, v9, v9 row_bcast:31 row_mask:0xc bank_mask:0xf
	s_nop 1
	v_readlane_b32 s79, v9, 63
	s_nop 1
	v_mov_b32_e32 v174, s79
	v_fmamk_f32 v174, v174, 0x3a000000, v177
	v_rsq_f32_e32 v176, v174
	s_nop 0
	v_mul_f32_e32 v5, v106, v176
	v_mul_f32_e32 v6, v107, v176
	v_mul_f32_e32 v7, v108, v176
	v_mul_f32_e32 v8, v109, v176
	v_fmac_f32_e32 v74, v5, v10
	v_fmac_f32_e32 v75, v6, v11
	v_fmac_f32_e32 v76, v7, v12
	v_fmac_f32_e32 v77, v8, v13
	v_mul_f32_e32 v5, v110, v176
	v_mul_f32_e32 v6, v111, v176
	v_mul_f32_e32 v7, v112, v176
	v_mul_f32_e32 v8, v113, v176
	v_fmac_f32_e32 v78, v5, v14
	v_fmac_f32_e32 v79, v6, v15
	v_fmac_f32_e32 v80, v7, v16
	v_fmac_f32_e32 v81, v8, v17
	v_mul_f32_e32 v5, v114, v176
	v_mul_f32_e32 v6, v115, v176
	v_mul_f32_e32 v7, v116, v176
	v_mul_f32_e32 v8, v117, v176
	v_fmac_f32_e32 v82, v5, v18
	v_fmac_f32_e32 v83, v6, v19
	v_fmac_f32_e32 v84, v7, v20
	v_fmac_f32_e32 v85, v8, v21
	v_mul_f32_e32 v5, v118, v176
	v_mul_f32_e32 v6, v119, v176
	v_mul_f32_e32 v7, v120, v176
	v_mul_f32_e32 v8, v121, v176
	v_fmac_f32_e32 v86, v5, v22
	v_fmac_f32_e32 v87, v6, v23
	v_fmac_f32_e32 v88, v7, v24
	v_fmac_f32_e32 v89, v8, v25
	v_mul_f32_e32 v5, v122, v176
	v_mul_f32_e32 v6, v123, v176
	v_mul_f32_e32 v7, v124, v176
	v_mul_f32_e32 v8, v125, v176
	v_fmac_f32_e32 v90, v5, v26
	v_fmac_f32_e32 v91, v6, v27
	v_fmac_f32_e32 v92, v7, v28
	v_fmac_f32_e32 v93, v8, v29
	v_mul_f32_e32 v5, v126, v176
	v_mul_f32_e32 v6, v127, v176
	v_mul_f32_e32 v7, v128, v176
	v_mul_f32_e32 v8, v129, v176
	v_fmac_f32_e32 v94, v5, v30
	v_fmac_f32_e32 v95, v6, v31
	v_fmac_f32_e32 v96, v7, v32
	v_fmac_f32_e32 v97, v8, v33
	v_mul_f32_e32 v5, v130, v176
	v_mul_f32_e32 v6, v131, v176
	v_mul_f32_e32 v7, v132, v176
	v_mul_f32_e32 v8, v133, v176
	v_fmac_f32_e32 v98, v5, v34
	v_fmac_f32_e32 v99, v6, v35
	v_fmac_f32_e32 v100, v7, v36
	v_fmac_f32_e32 v101, v8, v37
	v_mul_f32_e32 v5, v134, v176
	v_mul_f32_e32 v6, v135, v176
	v_mul_f32_e32 v7, v136, v176
	v_mul_f32_e32 v8, v137, v176
	v_fmac_f32_e32 v102, v5, v38
	v_fmac_f32_e32 v103, v6, v39
	v_fmac_f32_e32 v104, v7, v40
	v_fmac_f32_e32 v105, v8, v41
	s_add_u32 s97, s18, 0x4000
	s_lshl_b32 s34, s97, 13
	s_add_u32 s28, s8, s34
	s_addc_u32 s29, s9, 0
	global_store_dwordx4 v2, v[74:77], s[28:29] offset:0
	global_store_dwordx4 v2, v[78:81], s[28:29] offset:1024
	global_store_dwordx4 v2, v[82:85], s[28:29] offset:2048
	global_store_dwordx4 v2, v[86:89], s[28:29] offset:3072
	global_store_dwordx4 v3, v[90:93], s[28:29] offset:0
	global_store_dwordx4 v3, v[94:97], s[28:29] offset:1024
	global_store_dwordx4 v3, v[98:101], s[28:29] offset:2048
	global_store_dwordx4 v3, v[102:105], s[28:29] offset:3072
	v_mov_b32_e32 v9, 0
	v_mul_f32_e32 v174, v74, v74
	v_fmac_f32_e32 v174, v75, v75
	v_mul_f32_e32 v175, v76, v76
	v_fmac_f32_e32 v175, v77, v77
	v_add_f32_e32 v174, v174, v175
	v_add_f32_e32 v9, v9, v174
	v_mul_f32_e32 v174, v78, v78
	v_fmac_f32_e32 v174, v79, v79
	v_mul_f32_e32 v175, v80, v80
	v_fmac_f32_e32 v175, v81, v81
	v_add_f32_e32 v174, v174, v175
	v_add_f32_e32 v9, v9, v174
	v_mul_f32_e32 v174, v82, v82
	v_fmac_f32_e32 v174, v83, v83
	v_mul_f32_e32 v175, v84, v84
	v_fmac_f32_e32 v175, v85, v85
	v_add_f32_e32 v174, v174, v175
	v_add_f32_e32 v9, v9, v174
	v_mul_f32_e32 v174, v86, v86
	v_fmac_f32_e32 v174, v87, v87
	v_mul_f32_e32 v175, v88, v88
	v_fmac_f32_e32 v175, v89, v89
	v_add_f32_e32 v174, v174, v175
	v_add_f32_e32 v9, v9, v174
	v_mul_f32_e32 v174, v90, v90
	v_fmac_f32_e32 v174, v91, v91
	v_mul_f32_e32 v175, v92, v92
	v_fmac_f32_e32 v175, v93, v93
	v_add_f32_e32 v174, v174, v175
	v_add_f32_e32 v9, v9, v174
	v_mul_f32_e32 v174, v94, v94
	v_fmac_f32_e32 v174, v95, v95
	v_mul_f32_e32 v175, v96, v96
	v_fmac_f32_e32 v175, v97, v97
; __device__ __forceinline__ unsigned cvt_pk_bf16(float lo, float hi) { unsigned r; asm volatile("v_cvt_pk_bf16_f32 %0, %1, %2" : "=v"(r) : "v"(lo), "v"(hi)); return r; }
; __global__ void __launch_bounds__(512, 2) mega_fwd(Args a) {
;     ...
;         ss2 += (v[j].x * v[j].x + v[j].y * v[j].y) + (v[j].z * v[j].z + v[j].w * v[j].w); }
;       const float r2 = rsqrtf(wave_sum(ss2) * (1.f / DM) + EPS);
; #pragma unroll
;       for (int j = 0; j < 8; ++j) { const f32x4 gn = *(const f32x4*)(g2 + 4 * (64 * j + lane)); const f32x4 y = v[j] * r2 * gn;
;         u32x2 w; w.x = cvt_pk_bf16(y.x, y.y); w.y = cvt_pk_bf16(y.z, y.w); *(u32x2*)(XN + (size_t)m * DM + 4 * (64 * j + lane)) = w; }
;     }
	v_add_f32_e32 v174, v174, v175
	v_add_f32_e32 v9, v9, v174
	v_mul_f32_e32 v174, v98, v98
	v_fmac_f32_e32 v174, v99, v99
	v_mul_f32_e32 v175, v100, v100
	v_fmac_f32_e32 v175, v101, v101
	v_add_f32_e32 v174, v174, v175
	v_add_f32_e32 v9, v9, v174
	v_mul_f32_e32 v174, v102, v102
	v_fmac_f32_e32 v174, v103, v103
	v_mul_f32_e32 v175, v104, v104
	v_fmac_f32_e32 v175, v105, v105
	v_add_f32_e32 v174, v174, v175
	v_add_f32_e32 v9, v9, v174
	s_nop 1
	v_add_f32_dpp v9, v9, v9 quad_perm:[1,0,3,2] row_mask:0xf bank_mask:0xf
	s_nop 1
	v_add_f32_dpp v9, v9, v9 quad_perm:[2,3,0,1] row_mask:0xf bank_mask:0xf
	s_nop 1
	v_add_f32_dpp v9, v9, v9 row_half_mirror row_mask:0xf bank_mask:0xf
	s_nop 1
	v_add_f32_dpp v9, v9, v9 row_mirror row_mask:0xf bank_mask:0xf
	s_nop 1
	v_add_f32_dpp v9, v9, v9 row_bcast:15 row_mask:0xa bank_mask:0xf
	s_nop 1
	v_add_f32_dpp v9, v9, v9 row_bcast:31 row_mask:0xc bank_mask:0xf
	s_nop 1
	v_readlane_b32 s79, v9, 63
	s_nop 1
	v_mov_b32_e32 v174, s79
	v_fmamk_f32 v174, v174, 0x3a000000, v177
	v_rsq_f32_e32 v176, v174
	s_nop 0
	v_mul_f32_e32 v5, v74, v176
	v_mul_f32_e32 v6, v75, v176
	v_mul_f32_e32 v7, v76, v176
	v_mul_f32_e32 v8, v77, v176
	v_mul_f32_e32 v5, v5, v42
	v_mul_f32_e32 v6, v6, v43
	v_mul_f32_e32 v7, v7, v44
	v_mul_f32_e32 v8, v8, v45
	v_cvt_pk_bf16_f32 v138, v5, v6
	v_cvt_pk_bf16_f32 v139, v7, v8
	v_mul_f32_e32 v5, v78, v176
	v_mul_f32_e32 v6, v79, v176
	v_mul_f32_e32 v7, v80, v176
	v_mul_f32_e32 v8, v81, v176
	v_mul_f32_e32 v5, v5, v46
	v_mul_f32_e32 v6, v6, v47
	v_mul_f32_e32 v7, v7, v48
	v_mul_f32_e32 v8, v8, v49
	v_cvt_pk_bf16_f32 v140, v5, v6
	v_cvt_pk_bf16_f32 v141, v7, v8
	v_mul_f32_e32 v5, v82, v176
	v_mul_f32_e32 v6, v83, v176
	v_mul_f32_e32 v7, v84, v176
	v_mul_f32_e32 v8, v85, v176
	v_mul_f32_e32 v5, v5, v50
	v_mul_f32_e32 v6, v6, v51
	v_mul_f32_e32 v7, v7, v52
	v_mul_f32_e32 v8, v8, v53
	v_cvt_pk_bf16_f32 v142, v5, v6
	v_cvt_pk_bf16_f32 v143, v7, v8
	v_mul_f32_e32 v5, v86, v176
	v_mul_f32_e32 v6, v87, v176
	v_mul_f32_e32 v7, v88, v176
	v_mul_f32_e32 v8, v89, v176
	v_mul_f32_e32 v5, v5, v54
	v_mul_f32_e32 v6, v6, v55
	v_mul_f32_e32 v7, v7, v56
	v_mul_f32_e32 v8, v8, v57
	v_cvt_pk_bf16_f32 v144, v5, v6
	v_cvt_pk_bf16_f32 v145, v7, v8
	v_mul_f32_e32 v5, v90, v176
	v_mul_f32_e32 v6, v91, v176
	v_mul_f32_e32 v7, v92, v176
	v_mul_f32_e32 v8, v93, v176
	v_mul_f32_e32 v5, v5, v58
	v_mul_f32_e32 v6, v6, v59
	v_mul_f32_e32 v7, v7, v60
	v_mul_f32_e32 v8, v8, v61
	v_cvt_pk_bf16_f32 v146, v5, v6
	v_cvt_pk_bf16_f32 v147, v7, v8
	v_mul_f32_e32 v5, v94, v176
	v_mul_f32_e32 v6, v95, v176
	v_mul_f32_e32 v7, v96, v176
	v_mul_f32_e32 v8, v97, v176
	v_mul_f32_e32 v5, v5, v62
	v_mul_f32_e32 v6, v6, v63
	v_mul_f32_e32 v7, v7, v64
	v_mul_f32_e32 v8, v8, v65
	v_cvt_pk_bf16_f32 v148, v5, v6
	v_cvt_pk_bf16_f32 v149, v7, v8
	v_mul_f32_e32 v5, v98, v176
	v_mul_f32_e32 v6, v99, v176
	v_mul_f32_e32 v7, v100, v176
	v_mul_f32_e32 v8, v101, v176
	v_mul_f32_e32 v5, v5, v66
	v_mul_f32_e32 v6, v6, v67
	v_mul_f32_e32 v7, v7, v68
	v_mul_f32_e32 v8, v8, v69
	v_cvt_pk_bf16_f32 v150, v5, v6
	v_cvt_pk_bf16_f32 v151, v7, v8
	v_mul_f32_e32 v5, v102, v176
	v_mul_f32_e32 v6, v103, v176
	v_mul_f32_e32 v7, v104, v176
	v_mul_f32_e32 v8, v105, v176
	v_mul_f32_e32 v5, v5, v70
	v_mul_f32_e32 v6, v6, v71
	v_mul_f32_e32 v7, v7, v72
	v_mul_f32_e32 v8, v8, v73
	v_cvt_pk_bf16_f32 v152, v5, v6
	v_cvt_pk_bf16_f32 v153, v7, v8
	s_add_u32 s97, s18, 0x4000
	s_lshl_b32 s34, s97, 12
	s_add_u32 s28, s14, s34
	s_addc_u32 s29, s15, 0
	global_store_dwordx2 v4, v[138:139], s[28:29] offset:0
	global_store_dwordx2 v4, v[140:141], s[28:29] offset:512
	global_store_dwordx2 v4, v[142:143], s[28:29] offset:1024
	global_store_dwordx2 v4, v[144:145], s[28:29] offset:1536
	global_store_dwordx2 v4, v[146:147], s[28:29] offset:2048
	global_store_dwordx2 v4, v[148:149], s[28:29] offset:2560
	global_store_dwordx2 v4, v[150:151], s[28:29] offset:3072
	global_store_dwordx2 v4, v[152:153], s[28:29] offset:3584
	s_lshr_b32 s97, s78, 2
	s_add_u32 s18, s18, s97
	s_branch .Lew5_samp_loop
.Lew5_prompt:
	global_load_dwordx4 v[10:13], v2, s[20:21] offset:0
	global_load_dwordx4 v[14:17], v2, s[20:21] offset:1024
	global_load_dwordx4 v[18:21], v2, s[20:21] offset:2048
	global_load_dwordx4 v[22:25], v2, s[20:21] offset:3072
	global_load_dwordx4 v[26:29], v3, s[20:21] offset:0
	global_load_dwordx4 v[30:33], v3, s[20:21] offset:1024
	global_load_dwordx4 v[34:37], v3, s[20:21] offset:2048
	global_load_dwordx4 v[38:41], v3, s[20:21] offset:3072
	global_load_dwordx4 v[42:45], v2, s[22:23] offset:0
	global_load_dwordx4 v[46:49], v2, s[22:23] offset:1024
	global_load_dwordx4 v[50:53], v2, s[22:23] offset:2048
	global_load_dwordx4 v[54:57], v2, s[22:23] offset:3072
	global_load_dwordx4 v[58:61], v3, s[22:23] offset:0
	global_load_dwordx4 v[62:65], v3, s[22:23] offset:1024
	global_load_dwordx4 v[66:69], v3, s[22:23] offset:2048
	global_load_dwordx4 v[70:73], v3, s[22:23] offset:3072
	s_mov_b32 s18, s96
; __device__ __forceinline__ float bflo(unsigned w) { return __uint_as_float(w << 16); }
; __device__ __forceinline__ float bfhi(unsigned w) { return __uint_as_float(w & 0xffff0000u); }
; __global__ void __launch_bounds__(512, 2) mega_fwd(Args a) {
;     ...
;     for (int m = gw; m < MT; m += NGW) {
;       const float* xrow = m < MP ? x_p + (size_t)m * DM : x_s + (size_t)(m - MP) * DM;
;       f32x4 xin[8];
; #pragma unroll
;       for (int j = 0; j < 8; ++j) xin[j] = *(const f32x4*)(xrow + 4 * (64 * j + lane));
;       f32x4 v[8]; float ss = 0.f;
; #pragma unroll
;       for (int j = 0; j < 8; ++j) {
;         if (m < MP) { const u32x2 w = *(const u32x2*)(MO + (size_t)m * DM + 4 * (64 * j + lane)); v[j] = (f32x4){bflo(w.x), bfhi(w.x), bflo(w.y), bfhi(w.y)}; }
;         else { v[j] = (f32x4){0.f, 0.f, 0.f, 0.f};
; #pragma unroll
;           for (int ks = 0; ks < 16; ++ks) v[j] += *(const f32x4*)(PART + ((size_t)ks * MSAMP + (m - MP)) * DM + 4 * (64 * j + lane)); }
;         ss += (v[j].x * v[j].x + v[j].y * v[j].y) + (v[j].z * v[j].z + v[j].w * v[j].w); }
;       const float r = rsqrtf(wave_sum(ss) * (1.f / DM) + EPS); float ss2 = 0.f;
.Lew5_loop:
	s_cmpk_ge_u32 s18, 0x4000
	s_cbranch_scc1 .Lew5_done
	s_add_u32 s19, s18, s78
	s_lshl_b32 s97, s18, 13
	s_add_u32 s24, s4, s97
	s_addc_u32 s25, s5, 0
	s_lshl_b32 s97, s18, 12
	s_add_u32 s26, s12, s97
	s_addc_u32 s27, s13, 0
	global_load_dwordx4 v[74:77], v2, s[24:25] offset:0
	global_load_dwordx4 v[78:81], v2, s[24:25] offset:1024
	global_load_dwordx4 v[82:85], v2, s[24:25] offset:2048
	global_load_dwordx4 v[86:89], v2, s[24:25] offset:3072
	global_load_dwordx4 v[90:93], v3, s[24:25] offset:0
	global_load_dwordx4 v[94:97], v3, s[24:25] offset:1024
	global_load_dwordx4 v[98:101], v3, s[24:25] offset:2048
	global_load_dwordx4 v[102:105], v3, s[24:25] offset:3072
	global_load_dwordx2 v[138:139], v4, s[26:27] offset:0
	global_load_dwordx2 v[140:141], v4, s[26:27] offset:512
	global_load_dwordx2 v[142:143], v4, s[26:27] offset:1024
	global_load_dwordx2 v[144:145], v4, s[26:27] offset:1536
	global_load_dwordx2 v[146:147], v4, s[26:27] offset:2048
	global_load_dwordx2 v[148:149], v4, s[26:27] offset:2560
	global_load_dwordx2 v[150:151], v4, s[26:27] offset:3072
	global_load_dwordx2 v[152:153], v4, s[26:27] offset:3584
	s_cmpk_ge_u32 s19, 0x4000
	s_cbranch_scc1 .Lew5_single
	s_lshl_b32 s97, s19, 13
	s_add_u32 s28, s4, s97
	s_addc_u32 s29, s5, 0
	s_lshl_b32 s97, s19, 12
	s_add_u32 s30, s12, s97
	s_addc_u32 s31, s13, 0
	global_load_dwordx4 v[106:109], v2, s[28:29] offset:0
	global_load_dwordx4 v[110:113], v2, s[28:29] offset:1024
	global_load_dwordx4 v[114:117], v2, s[28:29] offset:2048
	global_load_dwordx4 v[118:121], v2, s[28:29] offset:3072
	global_load_dwordx4 v[122:125], v3, s[28:29] offset:0
	global_load_dwordx4 v[126:129], v3, s[28:29] offset:1024
	global_load_dwordx4 v[130:133], v3, s[28:29] offset:2048
	global_load_dwordx4 v[134:137], v3, s[28:29] offset:3072
	global_load_dwordx2 v[154:155], v4, s[30:31] offset:0
	global_load_dwordx2 v[156:157], v4, s[30:31] offset:512
	global_load_dwordx2 v[158:159], v4, s[30:31] offset:1024
	global_load_dwordx2 v[160:161], v4, s[30:31] offset:1536
	global_load_dwordx2 v[162:163], v4, s[30:31] offset:2048
	global_load_dwordx2 v[166:167], v4, s[30:31] offset:2560
	global_load_dwordx2 v[168:169], v4, s[30:31] offset:3072
	global_load_dwordx2 v[172:173], v4, s[30:31] offset:3584
	s_waitcnt vmcnt(16)
	v_mov_b32_e32 v9, 0
	v_lshlrev_b32_e32 v5, 16, v138
	v_and_b32_e32 v6, 0xffff0000, v138
	v_lshlrev_b32_e32 v7, 16, v139
	v_and_b32_e32 v8, 0xffff0000, v139
	v_mul_f32_e32 v174, v5, v5
	v_fmac_f32_e32 v174, v6, v6
	v_mul_f32_e32 v175, v7, v7
	v_fmac_f32_e32 v175, v8, v8
	v_add_f32_e32 v174, v174, v175
	v_add_f32_e32 v9, v9, v174
	v_lshlrev_b32_e32 v5, 16, v140
	v_and_b32_e32 v6, 0xffff0000, v140
	v_lshlrev_b32_e32 v7, 16, v141
	v_and_b32_e32 v8, 0xffff0000, v141
	v_mul_f32_e32 v174, v5, v5
	v_fmac_f32_e32 v174, v6, v6
	v_mul_f32_e32 v175, v7, v7
	v_fmac_f32_e32 v175, v8, v8
	v_add_f32_e32 v174, v174, v175
	v_add_f32_e32 v9, v9, v174
	v_lshlrev_b32_e32 v5, 16, v142
	v_and_b32_e32 v6, 0xffff0000, v142
	v_lshlrev_b32_e32 v7, 16, v143
	v_and_b32_e32 v8, 0xffff0000, v143
	v_mul_f32_e32 v174, v5, v5
	v_fmac_f32_e32 v174, v6, v6
	v_mul_f32_e32 v175, v7, v7
	v_fmac_f32_e32 v175, v8, v8
	v_add_f32_e32 v174, v174, v175
	v_add_f32_e32 v9, v9, v174
	v_lshlrev_b32_e32 v5, 16, v144
	v_and_b32_e32 v6, 0xffff0000, v144
	v_lshlrev_b32_e32 v7, 16, v145
	v_and_b32_e32 v8, 0xffff0000, v145
	v_mul_f32_e32 v174, v5, v5
	v_fmac_f32_e32 v174, v6, v6
	v_mul_f32_e32 v175, v7, v7
	v_fmac_f32_e32 v175, v8, v8
	v_add_f32_e32 v174, v174, v175
	v_add_f32_e32 v9, v9, v174
	v_lshlrev_b32_e32 v5, 16, v146
	v_and_b32_e32 v6, 0xffff0000, v146
	v_lshlrev_b32_e32 v7, 16, v147
	v_and_b32_e32 v8, 0xffff0000, v147
	v_mul_f32_e32 v174, v5, v5
	v_fmac_f32_e32 v174, v6, v6
	v_mul_f32_e32 v175, v7, v7
	v_fmac_f32_e32 v175, v8, v8
	v_add_f32_e32 v174, v174, v175
	v_add_f32_e32 v9, v9, v174
	v_lshlrev_b32_e32 v5, 16, v148
	v_and_b32_e32 v6, 0xffff0000, v148
	v_lshlrev_b32_e32 v7, 16, v149
	v_and_b32_e32 v8, 0xffff0000, v149
	v_mul_f32_e32 v174, v5, v5
	v_fmac_f32_e32 v174, v6, v6
	v_mul_f32_e32 v175, v7, v7
	v_fmac_f32_e32 v175, v8, v8
	v_add_f32_e32 v174, v174, v175
	v_add_f32_e32 v9, v9, v174
	v_lshlrev_b32_e32 v5, 16, v150
	v_and_b32_e32 v6, 0xffff0000, v150
	v_lshlrev_b32_e32 v7, 16, v151
	v_and_b32_e32 v8, 0xffff0000, v151
	v_mul_f32_e32 v174, v5, v5
	v_fmac_f32_e32 v174, v6, v6
	v_mul_f32_e32 v175, v7, v7
	v_fmac_f32_e32 v175, v8, v8
	v_add_f32_e32 v174, v174, v175
	v_add_f32_e32 v9, v9, v174
	v_lshlrev_b32_e32 v5, 16, v152
	v_and_b32_e32 v6, 0xffff0000, v152
	v_lshlrev_b32_e32 v7, 16, v153
	v_and_b32_e32 v8, 0xffff0000, v153
	v_mul_f32_e32 v174, v5, v5
	v_fmac_f32_e32 v174, v6, v6
	v_mul_f32_e32 v175, v7, v7
	v_fmac_f32_e32 v175, v8, v8
	v_add_f32_e32 v174, v174, v175
	v_add_f32_e32 v9, v9, v174
	s_nop 1
	v_add_f32_dpp v9, v9, v9 quad_perm:[1,0,3,2] row_mask:0xf bank_mask:0xf
	s_nop 1
	v_add_f32_dpp v9, v9, v9 quad_perm:[2,3,0,1] row_mask:0xf bank_mask:0xf
	s_nop 1
	v_add_f32_dpp v9, v9, v9 row_half_mirror row_mask:0xf bank_mask:0xf
	s_nop 1
	v_add_f32_dpp v9, v9, v9 row_mirror row_mask:0xf bank_mask:0xf
	s_nop 1
	v_add_f32_dpp v9, v9, v9 row_bcast:15 row_mask:0xa bank_mask:0xf
	s_nop 1
	v_add_f32_dpp v9, v9, v9 row_bcast:31 row_mask:0xc bank_mask:0xf
	s_nop 1
	v_readlane_b32 s79, v9, 63
	s_nop 1
	v_mov_b32_e32 v174, s79
	v_fmamk_f32 v174, v174, 0x3a000000, v177
	v_rsq_f32_e32 v176, v174
	s_nop 0
	v_lshlrev_b32_e32 v5, 16, v138
	v_and_b32_e32 v6, 0xffff0000, v138
	v_lshlrev_b32_e32 v7, 16, v139
	v_and_b32_e32 v8, 0xffff0000, v139
	v_mul_f32_e32 v5, v5, v176
	v_mul_f32_e32 v6, v6, v176
	v_mul_f32_e32 v7, v7, v176
	v_mul_f32_e32 v8, v8, v176
; __global__ void __launch_bounds__(512, 2) mega_fwd(Args a) {
;     ...
;       const float r = rsqrtf(wave_sum(ss) * (1.f / DM) + EPS); float ss2 = 0.f;
; #pragma unroll
;       for (int j = 0; j < 8; ++j) { const f32x4 gn = *(const f32x4*)(g1 + 4 * (64 * j + lane)); const f32x4 xv = xin[j];
;         v[j] = xv + v[j] * r * gn; *(f32x4*)(out + O_Y + (size_t)m * DM + 4 * (64 * j + lane)) = v[j];
;         ss2 += (v[j].x * v[j].x + v[j].y * v[j].y) + (v[j].z * v[j].z + v[j].w * v[j].w); }
;       const float r2 = rsqrtf(wave_sum(ss2) * (1.f / DM) + EPS);
; #pragma unroll
;       for (int j = 0; j < 8; ++j) { const f32x4 gn = *(const f32x4*)(g2 + 4 * (64 * j + lane)); const f32x4 y = v[j] * r2 * gn;
	v_fmac_f32_e32 v74, v5, v10
	v_fmac_f32_e32 v75, v6, v11
	v_fmac_f32_e32 v76, v7, v12
	v_fmac_f32_e32 v77, v8, v13
	v_lshlrev_b32_e32 v5, 16, v140
	v_and_b32_e32 v6, 0xffff0000, v140
	v_lshlrev_b32_e32 v7, 16, v141
	v_and_b32_e32 v8, 0xffff0000, v141
	v_mul_f32_e32 v5, v5, v176
	v_mul_f32_e32 v6, v6, v176
	v_mul_f32_e32 v7, v7, v176
	v_mul_f32_e32 v8, v8, v176
	v_fmac_f32_e32 v78, v5, v14
	v_fmac_f32_e32 v79, v6, v15
	v_fmac_f32_e32 v80, v7, v16
	v_fmac_f32_e32 v81, v8, v17
	v_lshlrev_b32_e32 v5, 16, v142
	v_and_b32_e32 v6, 0xffff0000, v142
	v_lshlrev_b32_e32 v7, 16, v143
	v_and_b32_e32 v8, 0xffff0000, v143
	v_mul_f32_e32 v5, v5, v176
	v_mul_f32_e32 v6, v6, v176
	v_mul_f32_e32 v7, v7, v176
	v_mul_f32_e32 v8, v8, v176
	v_fmac_f32_e32 v82, v5, v18
	v_fmac_f32_e32 v83, v6, v19
	v_fmac_f32_e32 v84, v7, v20
	v_fmac_f32_e32 v85, v8, v21
	v_lshlrev_b32_e32 v5, 16, v144
	v_and_b32_e32 v6, 0xffff0000, v144
	v_lshlrev_b32_e32 v7, 16, v145
	v_and_b32_e32 v8, 0xffff0000, v145
	v_mul_f32_e32 v5, v5, v176
	v_mul_f32_e32 v6, v6, v176
	v_mul_f32_e32 v7, v7, v176
	v_mul_f32_e32 v8, v8, v176
	v_fmac_f32_e32 v86, v5, v22
	v_fmac_f32_e32 v87, v6, v23
	v_fmac_f32_e32 v88, v7, v24
	v_fmac_f32_e32 v89, v8, v25
	v_lshlrev_b32_e32 v5, 16, v146
	v_and_b32_e32 v6, 0xffff0000, v146
	v_lshlrev_b32_e32 v7, 16, v147
	v_and_b32_e32 v8, 0xffff0000, v147
	v_mul_f32_e32 v5, v5, v176
	v_mul_f32_e32 v6, v6, v176
	v_mul_f32_e32 v7, v7, v176
	v_mul_f32_e32 v8, v8, v176
	v_fmac_f32_e32 v90, v5, v26
	v_fmac_f32_e32 v91, v6, v27
	v_fmac_f32_e32 v92, v7, v28
	v_fmac_f32_e32 v93, v8, v29
	v_lshlrev_b32_e32 v5, 16, v148
	v_and_b32_e32 v6, 0xffff0000, v148
	v_lshlrev_b32_e32 v7, 16, v149
	v_and_b32_e32 v8, 0xffff0000, v149
	v_mul_f32_e32 v5, v5, v176
	v_mul_f32_e32 v6, v6, v176
	v_mul_f32_e32 v7, v7, v176
	v_mul_f32_e32 v8, v8, v176
	v_fmac_f32_e32 v94, v5, v30
	v_fmac_f32_e32 v95, v6, v31
	v_fmac_f32_e32 v96, v7, v32
	v_fmac_f32_e32 v97, v8, v33
	v_lshlrev_b32_e32 v5, 16, v150
	v_and_b32_e32 v6, 0xffff0000, v150
	v_lshlrev_b32_e32 v7, 16, v151
	v_and_b32_e32 v8, 0xffff0000, v151
	v_mul_f32_e32 v5, v5, v176
	v_mul_f32_e32 v6, v6, v176
	v_mul_f32_e32 v7, v7, v176
	v_mul_f32_e32 v8, v8, v176
	v_fmac_f32_e32 v98, v5, v34
	v_fmac_f32_e32 v99, v6, v35
	v_fmac_f32_e32 v100, v7, v36
	v_fmac_f32_e32 v101, v8, v37
	v_lshlrev_b32_e32 v5, 16, v152
	v_and_b32_e32 v6, 0xffff0000, v152
	v_lshlrev_b32_e32 v7, 16, v153
	v_and_b32_e32 v8, 0xffff0000, v153
	v_mul_f32_e32 v5, v5, v176
	v_mul_f32_e32 v6, v6, v176
	v_mul_f32_e32 v7, v7, v176
	v_mul_f32_e32 v8, v8, v176
	v_fmac_f32_e32 v102, v5, v38
	v_fmac_f32_e32 v103, v6, v39
	v_fmac_f32_e32 v104, v7, v40
	v_fmac_f32_e32 v105, v8, v41
	s_lshl_b32 s97, s18, 13
	s_add_u32 s24, s8, s97
	s_addc_u32 s25, s9, 0
	global_store_dwordx4 v2, v[74:77], s[24:25] offset:0
	global_store_dwordx4 v2, v[78:81], s[24:25] offset:1024
	global_store_dwordx4 v2, v[82:85], s[24:25] offset:2048
	global_store_dwordx4 v2, v[86:89], s[24:25] offset:3072
	global_store_dwordx4 v3, v[90:93], s[24:25] offset:0
	global_store_dwordx4 v3, v[94:97], s[24:25] offset:1024
	global_store_dwordx4 v3, v[98:101], s[24:25] offset:2048
	global_store_dwordx4 v3, v[102:105], s[24:25] offset:3072
	v_mov_b32_e32 v9, 0
	v_mul_f32_e32 v174, v74, v74
	v_fmac_f32_e32 v174, v75, v75
	v_mul_f32_e32 v175, v76, v76
	v_fmac_f32_e32 v175, v77, v77
	v_add_f32_e32 v174, v174, v175
	v_add_f32_e32 v9, v9, v174
	v_mul_f32_e32 v174, v78, v78
	v_fmac_f32_e32 v174, v79, v79
	v_mul_f32_e32 v175, v80, v80
	v_fmac_f32_e32 v175, v81, v81
	v_add_f32_e32 v174, v174, v175
	v_add_f32_e32 v9, v9, v174
	v_mul_f32_e32 v174, v82, v82
	v_fmac_f32_e32 v174, v83, v83
	v_mul_f32_e32 v175, v84, v84
	v_fmac_f32_e32 v175, v85, v85
	v_add_f32_e32 v174, v174, v175
	v_add_f32_e32 v9, v9, v174
	v_mul_f32_e32 v174, v86, v86
	v_fmac_f32_e32 v174, v87, v87
	v_mul_f32_e32 v175, v88, v88
	v_fmac_f32_e32 v175, v89, v89
	v_add_f32_e32 v174, v174, v175
	v_add_f32_e32 v9, v9, v174
	v_mul_f32_e32 v174, v90, v90
	v_fmac_f32_e32 v174, v91, v91
	v_mul_f32_e32 v175, v92, v92
	v_fmac_f32_e32 v175, v93, v93
	v_add_f32_e32 v174, v174, v175
	v_add_f32_e32 v9, v9, v174
	v_mul_f32_e32 v174, v94, v94
	v_fmac_f32_e32 v174, v95, v95
	v_mul_f32_e32 v175, v96, v96
	v_fmac_f32_e32 v175, v97, v97
	v_add_f32_e32 v174, v174, v175
	v_add_f32_e32 v9, v9, v174
	v_mul_f32_e32 v174, v98, v98
	v_fmac_f32_e32 v174, v99, v99
	v_mul_f32_e32 v175, v100, v100
	v_fmac_f32_e32 v175, v101, v101
	v_add_f32_e32 v174, v174, v175
	v_add_f32_e32 v9, v9, v174
	v_mul_f32_e32 v174, v102, v102
	v_fmac_f32_e32 v174, v103, v103
	v_mul_f32_e32 v175, v104, v104
	v_fmac_f32_e32 v175, v105, v105
	v_add_f32_e32 v174, v174, v175
	v_add_f32_e32 v9, v9, v174
	s_nop 1
	v_add_f32_dpp v9, v9, v9 quad_perm:[1,0,3,2] row_mask:0xf bank_mask:0xf
	s_nop 1
	v_add_f32_dpp v9, v9, v9 quad_perm:[2,3,0,1] row_mask:0xf bank_mask:0xf
	s_nop 1
	v_add_f32_dpp v9, v9, v9 row_half_mirror row_mask:0xf bank_mask:0xf
	s_nop 1
	v_add_f32_dpp v9, v9, v9 row_mirror row_mask:0xf bank_mask:0xf
	s_nop 1
	v_add_f32_dpp v9, v9, v9 row_bcast:15 row_mask:0xa bank_mask:0xf
	s_nop 1
	v_add_f32_dpp v9, v9, v9 row_bcast:31 row_mask:0xc bank_mask:0xf
	s_nop 1
	v_readlane_b32 s79, v9, 63
	s_nop 1
	v_mov_b32_e32 v174, s79
	v_fmamk_f32 v174, v174, 0x3a000000, v177
	v_rsq_f32_e32 v176, v174
	s_nop 0
	v_mul_f32_e32 v5, v74, v176
	v_mul_f32_e32 v6, v75, v176
	v_mul_f32_e32 v7, v76, v176
	v_mul_f32_e32 v8, v77, v176
	v_mul_f32_e32 v5, v5, v42
	v_mul_f32_e32 v6, v6, v43
	v_mul_f32_e32 v7, v7, v44
	v_mul_f32_e32 v8, v8, v45
	v_cvt_pk_bf16_f32 v138, v5, v6
	v_cvt_pk_bf16_f32 v139, v7, v8
	v_mul_f32_e32 v5, v78, v176
	v_mul_f32_e32 v6, v79, v176
; __device__ __forceinline__ unsigned cvt_pk_bf16(float lo, float hi) { unsigned r; asm volatile("v_cvt_pk_bf16_f32 %0, %1, %2" : "=v"(r) : "v"(lo), "v"(hi)); return r; }
; __device__ __forceinline__ float bflo(unsigned w) { return __uint_as_float(w << 16); }
; __device__ __forceinline__ float bfhi(unsigned w) { return __uint_as_float(w & 0xffff0000u); }
; __global__ void __launch_bounds__(512, 2) mega_fwd(Args a) {
;     ...
;       for (int j = 0; j < 8; ++j) {
;         if (m < MP) { const u32x2 w = *(const u32x2*)(MO + (size_t)m * DM + 4 * (64 * j + lane)); v[j] = (f32x4){bflo(w.x), bfhi(w.x), bflo(w.y), bfhi(w.y)}; }
;         else { v[j] = (f32x4){0.f, 0.f, 0.f, 0.f};
; #pragma unroll
;           for (int ks = 0; ks < 16; ++ks) v[j] += *(const f32x4*)(PART + ((size_t)ks * MSAMP + (m - MP)) * DM + 4 * (64 * j + lane)); }
;         ss += (v[j].x * v[j].x + v[j].y * v[j].y) + (v[j].z * v[j].z + v[j].w * v[j].w); }
;       const float r = rsqrtf(wave_sum(ss) * (1.f / DM) + EPS); float ss2 = 0.f;
;     ...
;       for (int j = 0; j < 8; ++j) { const f32x4 gn = *(const f32x4*)(g2 + 4 * (64 * j + lane)); const f32x4 y = v[j] * r2 * gn;
;         u32x2 w; w.x = cvt_pk_bf16(y.x, y.y); w.y = cvt_pk_bf16(y.z, y.w); *(u32x2*)(XN + (size_t)m * DM + 4 * (64 * j + lane)) = w; }
	v_mul_f32_e32 v7, v80, v176
	v_mul_f32_e32 v8, v81, v176
	v_mul_f32_e32 v5, v5, v46
	v_mul_f32_e32 v6, v6, v47
	v_mul_f32_e32 v7, v7, v48
	v_mul_f32_e32 v8, v8, v49
	v_cvt_pk_bf16_f32 v140, v5, v6
	v_cvt_pk_bf16_f32 v141, v7, v8
	v_mul_f32_e32 v5, v82, v176
	v_mul_f32_e32 v6, v83, v176
	v_mul_f32_e32 v7, v84, v176
	v_mul_f32_e32 v8, v85, v176
	v_mul_f32_e32 v5, v5, v50
	v_mul_f32_e32 v6, v6, v51
	v_mul_f32_e32 v7, v7, v52
	v_mul_f32_e32 v8, v8, v53
	v_cvt_pk_bf16_f32 v142, v5, v6
	v_cvt_pk_bf16_f32 v143, v7, v8
	v_mul_f32_e32 v5, v86, v176
	v_mul_f32_e32 v6, v87, v176
	v_mul_f32_e32 v7, v88, v176
	v_mul_f32_e32 v8, v89, v176
	v_mul_f32_e32 v5, v5, v54
	v_mul_f32_e32 v6, v6, v55
	v_mul_f32_e32 v7, v7, v56
	v_mul_f32_e32 v8, v8, v57
	v_cvt_pk_bf16_f32 v144, v5, v6
	v_cvt_pk_bf16_f32 v145, v7, v8
	v_mul_f32_e32 v5, v90, v176
	v_mul_f32_e32 v6, v91, v176
	v_mul_f32_e32 v7, v92, v176
	v_mul_f32_e32 v8, v93, v176
	v_mul_f32_e32 v5, v5, v58
	v_mul_f32_e32 v6, v6, v59
	v_mul_f32_e32 v7, v7, v60
	v_mul_f32_e32 v8, v8, v61
	v_cvt_pk_bf16_f32 v146, v5, v6
	v_cvt_pk_bf16_f32 v147, v7, v8
	v_mul_f32_e32 v5, v94, v176
	v_mul_f32_e32 v6, v95, v176
	v_mul_f32_e32 v7, v96, v176
	v_mul_f32_e32 v8, v97, v176
	v_mul_f32_e32 v5, v5, v62
	v_mul_f32_e32 v6, v6, v63
	v_mul_f32_e32 v7, v7, v64
	v_mul_f32_e32 v8, v8, v65
	v_cvt_pk_bf16_f32 v148, v5, v6
	v_cvt_pk_bf16_f32 v149, v7, v8
	v_mul_f32_e32 v5, v98, v176
	v_mul_f32_e32 v6, v99, v176
	v_mul_f32_e32 v7, v100, v176
	v_mul_f32_e32 v8, v101, v176
	v_mul_f32_e32 v5, v5, v66
	v_mul_f32_e32 v6, v6, v67
	v_mul_f32_e32 v7, v7, v68
	v_mul_f32_e32 v8, v8, v69
	v_cvt_pk_bf16_f32 v150, v5, v6
	v_cvt_pk_bf16_f32 v151, v7, v8
	v_mul_f32_e32 v5, v102, v176
	v_mul_f32_e32 v6, v103, v176
	v_mul_f32_e32 v7, v104, v176
	v_mul_f32_e32 v8, v105, v176
	v_mul_f32_e32 v5, v5, v70
	v_mul_f32_e32 v6, v6, v71
	v_mul_f32_e32 v7, v7, v72
	v_mul_f32_e32 v8, v8, v73
	v_cvt_pk_bf16_f32 v152, v5, v6
	v_cvt_pk_bf16_f32 v153, v7, v8
	s_lshl_b32 s97, s18, 12
	s_add_u32 s26, s14, s97
	s_addc_u32 s27, s15, 0
	global_store_dwordx2 v4, v[138:139], s[26:27] offset:0
	global_store_dwordx2 v4, v[140:141], s[26:27] offset:512
	global_store_dwordx2 v4, v[142:143], s[26:27] offset:1024
	global_store_dwordx2 v4, v[144:145], s[26:27] offset:1536
	global_store_dwordx2 v4, v[146:147], s[26:27] offset:2048
	global_store_dwordx2 v4, v[148:149], s[26:27] offset:2560
	global_store_dwordx2 v4, v[150:151], s[26:27] offset:3072
	global_store_dwordx2 v4, v[152:153], s[26:27] offset:3584
	s_waitcnt vmcnt(16)
	v_mov_b32_e32 v9, 0
	v_lshlrev_b32_e32 v5, 16, v154
	v_and_b32_e32 v6, 0xffff0000, v154
	v_lshlrev_b32_e32 v7, 16, v155
	v_and_b32_e32 v8, 0xffff0000, v155
	v_mul_f32_e32 v174, v5, v5
	v_fmac_f32_e32 v174, v6, v6
	v_mul_f32_e32 v175, v7, v7
	v_fmac_f32_e32 v175, v8, v8
	v_add_f32_e32 v174, v174, v175
	v_add_f32_e32 v9, v9, v174
	v_lshlrev_b32_e32 v5, 16, v156
	v_and_b32_e32 v6, 0xffff0000, v156
	v_lshlrev_b32_e32 v7, 16, v157
	v_and_b32_e32 v8, 0xffff0000, v157
	v_mul_f32_e32 v174, v5, v5
	v_fmac_f32_e32 v174, v6, v6
	v_mul_f32_e32 v175, v7, v7
	v_fmac_f32_e32 v175, v8, v8
	v_add_f32_e32 v174, v174, v175
	v_add_f32_e32 v9, v9, v174
	v_lshlrev_b32_e32 v5, 16, v158
	v_and_b32_e32 v6, 0xffff0000, v158
	v_lshlrev_b32_e32 v7, 16, v159
	v_and_b32_e32 v8, 0xffff0000, v159
	v_mul_f32_e32 v174, v5, v5
	v_fmac_f32_e32 v174, v6, v6
	v_mul_f32_e32 v175, v7, v7
	v_fmac_f32_e32 v175, v8, v8
	v_add_f32_e32 v174, v174, v175
	v_add_f32_e32 v9, v9, v174
	v_lshlrev_b32_e32 v5, 16, v160
	v_and_b32_e32 v6, 0xffff0000, v160
	v_lshlrev_b32_e32 v7, 16, v161
	v_and_b32_e32 v8, 0xffff0000, v161
	v_mul_f32_e32 v174, v5, v5
	v_fmac_f32_e32 v174, v6, v6
	v_mul_f32_e32 v175, v7, v7
	v_fmac_f32_e32 v175, v8, v8
	v_add_f32_e32 v174, v174, v175
	v_add_f32_e32 v9, v9, v174
	v_lshlrev_b32_e32 v5, 16, v162
	v_and_b32_e32 v6, 0xffff0000, v162
	v_lshlrev_b32_e32 v7, 16, v163
	v_and_b32_e32 v8, 0xffff0000, v163
	v_mul_f32_e32 v174, v5, v5
	v_fmac_f32_e32 v174, v6, v6
	v_mul_f32_e32 v175, v7, v7
	v_fmac_f32_e32 v175, v8, v8
	v_add_f32_e32 v174, v174, v175
	v_add_f32_e32 v9, v9, v174
	v_lshlrev_b32_e32 v5, 16, v166
	v_and_b32_e32 v6, 0xffff0000, v166
	v_lshlrev_b32_e32 v7, 16, v167
	v_and_b32_e32 v8, 0xffff0000, v167
	v_mul_f32_e32 v174, v5, v5
	v_fmac_f32_e32 v174, v6, v6
	v_mul_f32_e32 v175, v7, v7
	v_fmac_f32_e32 v175, v8, v8
	v_add_f32_e32 v174, v174, v175
	v_add_f32_e32 v9, v9, v174
	v_lshlrev_b32_e32 v5, 16, v168
	v_and_b32_e32 v6, 0xffff0000, v168
	v_lshlrev_b32_e32 v7, 16, v169
	v_and_b32_e32 v8, 0xffff0000, v169
	v_mul_f32_e32 v174, v5, v5
	v_fmac_f32_e32 v174, v6, v6
	v_mul_f32_e32 v175, v7, v7
	v_fmac_f32_e32 v175, v8, v8
	v_add_f32_e32 v174, v174, v175
	v_add_f32_e32 v9, v9, v174
	v_lshlrev_b32_e32 v5, 16, v172
	v_and_b32_e32 v6, 0xffff0000, v172
	v_lshlrev_b32_e32 v7, 16, v173
	v_and_b32_e32 v8, 0xffff0000, v173
	v_mul_f32_e32 v174, v5, v5
	v_fmac_f32_e32 v174, v6, v6
	v_mul_f32_e32 v175, v7, v7
	v_fmac_f32_e32 v175, v8, v8
	v_add_f32_e32 v174, v174, v175
	v_add_f32_e32 v9, v9, v174
	s_nop 1
	v_add_f32_dpp v9, v9, v9 quad_perm:[1,0,3,2] row_mask:0xf bank_mask:0xf
	s_nop 1
	v_add_f32_dpp v9, v9, v9 quad_perm:[2,3,0,1] row_mask:0xf bank_mask:0xf
	s_nop 1
	v_add_f32_dpp v9, v9, v9 row_half_mirror row_mask:0xf bank_mask:0xf
	s_nop 1
	v_add_f32_dpp v9, v9, v9 row_mirror row_mask:0xf bank_mask:0xf
	s_nop 1
	v_add_f32_dpp v9, v9, v9 row_bcast:15 row_mask:0xa bank_mask:0xf
	s_nop 1
	v_add_f32_dpp v9, v9, v9 row_bcast:31 row_mask:0xc bank_mask:0xf
	s_nop 1
	v_readlane_b32 s79, v9, 63
	s_nop 1
	v_mov_b32_e32 v174, s79
	v_fmamk_f32 v174, v174, 0x3a000000, v177
	v_rsq_f32_e32 v176, v174
	s_nop 0
; __global__ void __launch_bounds__(512, 2) mega_fwd(Args a) {
;     ...
;       const float r = rsqrtf(wave_sum(ss) * (1.f / DM) + EPS); float ss2 = 0.f;
; #pragma unroll
;       for (int j = 0; j < 8; ++j) { const f32x4 gn = *(const f32x4*)(g1 + 4 * (64 * j + lane)); const f32x4 xv = xin[j];
;         v[j] = xv + v[j] * r * gn; *(f32x4*)(out + O_Y + (size_t)m * DM + 4 * (64 * j + lane)) = v[j];
;         ss2 += (v[j].x * v[j].x + v[j].y * v[j].y) + (v[j].z * v[j].z + v[j].w * v[j].w); }
;       const float r2 = rsqrtf(wave_sum(ss2) * (1.f / DM) + EPS);
	v_lshlrev_b32_e32 v5, 16, v154
	v_and_b32_e32 v6, 0xffff0000, v154
	v_lshlrev_b32_e32 v7, 16, v155
	v_and_b32_e32 v8, 0xffff0000, v155
	v_mul_f32_e32 v5, v5, v176
	v_mul_f32_e32 v6, v6, v176
	v_mul_f32_e32 v7, v7, v176
	v_mul_f32_e32 v8, v8, v176
	v_fmac_f32_e32 v106, v5, v10
	v_fmac_f32_e32 v107, v6, v11
	v_fmac_f32_e32 v108, v7, v12
	v_fmac_f32_e32 v109, v8, v13
	v_lshlrev_b32_e32 v5, 16, v156
	v_and_b32_e32 v6, 0xffff0000, v156
	v_lshlrev_b32_e32 v7, 16, v157
	v_and_b32_e32 v8, 0xffff0000, v157
	v_mul_f32_e32 v5, v5, v176
	v_mul_f32_e32 v6, v6, v176
	v_mul_f32_e32 v7, v7, v176
	v_mul_f32_e32 v8, v8, v176
	v_fmac_f32_e32 v110, v5, v14
	v_fmac_f32_e32 v111, v6, v15
	v_fmac_f32_e32 v112, v7, v16
	v_fmac_f32_e32 v113, v8, v17
	v_lshlrev_b32_e32 v5, 16, v158
	v_and_b32_e32 v6, 0xffff0000, v158
	v_lshlrev_b32_e32 v7, 16, v159
	v_and_b32_e32 v8, 0xffff0000, v159
	v_mul_f32_e32 v5, v5, v176
	v_mul_f32_e32 v6, v6, v176
	v_mul_f32_e32 v7, v7, v176
	v_mul_f32_e32 v8, v8, v176
	v_fmac_f32_e32 v114, v5, v18
	v_fmac_f32_e32 v115, v6, v19
	v_fmac_f32_e32 v116, v7, v20
	v_fmac_f32_e32 v117, v8, v21
	v_lshlrev_b32_e32 v5, 16, v160
	v_and_b32_e32 v6, 0xffff0000, v160
	v_lshlrev_b32_e32 v7, 16, v161
	v_and_b32_e32 v8, 0xffff0000, v161
	v_mul_f32_e32 v5, v5, v176
	v_mul_f32_e32 v6, v6, v176
	v_mul_f32_e32 v7, v7, v176
	v_mul_f32_e32 v8, v8, v176
	v_fmac_f32_e32 v118, v5, v22
	v_fmac_f32_e32 v119, v6, v23
	v_fmac_f32_e32 v120, v7, v24
	v_fmac_f32_e32 v121, v8, v25
	v_lshlrev_b32_e32 v5, 16, v162
	v_and_b32_e32 v6, 0xffff0000, v162
	v_lshlrev_b32_e32 v7, 16, v163
	v_and_b32_e32 v8, 0xffff0000, v163
	v_mul_f32_e32 v5, v5, v176
	v_mul_f32_e32 v6, v6, v176
	v_mul_f32_e32 v7, v7, v176
	v_mul_f32_e32 v8, v8, v176
	v_fmac_f32_e32 v122, v5, v26
	v_fmac_f32_e32 v123, v6, v27
	v_fmac_f32_e32 v124, v7, v28
	v_fmac_f32_e32 v125, v8, v29
	v_lshlrev_b32_e32 v5, 16, v166
	v_and_b32_e32 v6, 0xffff0000, v166
	v_lshlrev_b32_e32 v7, 16, v167
	v_and_b32_e32 v8, 0xffff0000, v167
	v_mul_f32_e32 v5, v5, v176
	v_mul_f32_e32 v6, v6, v176
	v_mul_f32_e32 v7, v7, v176
	v_mul_f32_e32 v8, v8, v176
	v_fmac_f32_e32 v126, v5, v30
	v_fmac_f32_e32 v127, v6, v31
	v_fmac_f32_e32 v128, v7, v32
	v_fmac_f32_e32 v129, v8, v33
	v_lshlrev_b32_e32 v5, 16, v168
	v_and_b32_e32 v6, 0xffff0000, v168
	v_lshlrev_b32_e32 v7, 16, v169
	v_and_b32_e32 v8, 0xffff0000, v169
	v_mul_f32_e32 v5, v5, v176
	v_mul_f32_e32 v6, v6, v176
	v_mul_f32_e32 v7, v7, v176
	v_mul_f32_e32 v8, v8, v176
	v_fmac_f32_e32 v130, v5, v34
	v_fmac_f32_e32 v131, v6, v35
	v_fmac_f32_e32 v132, v7, v36
	v_fmac_f32_e32 v133, v8, v37
	v_lshlrev_b32_e32 v5, 16, v172
	v_and_b32_e32 v6, 0xffff0000, v172
	v_lshlrev_b32_e32 v7, 16, v173
	v_and_b32_e32 v8, 0xffff0000, v173
	v_mul_f32_e32 v5, v5, v176
	v_mul_f32_e32 v6, v6, v176
	v_mul_f32_e32 v7, v7, v176
	v_mul_f32_e32 v8, v8, v176
	v_fmac_f32_e32 v134, v5, v38
	v_fmac_f32_e32 v135, v6, v39
	v_fmac_f32_e32 v136, v7, v40
	v_fmac_f32_e32 v137, v8, v41
	s_lshl_b32 s97, s19, 13
	s_add_u32 s28, s8, s97
	s_addc_u32 s29, s9, 0
	global_store_dwordx4 v2, v[106:109], s[28:29] offset:0
	global_store_dwordx4 v2, v[110:113], s[28:29] offset:1024
	global_store_dwordx4 v2, v[114:117], s[28:29] offset:2048
	global_store_dwordx4 v2, v[118:121], s[28:29] offset:3072
	global_store_dwordx4 v3, v[122:125], s[28:29] offset:0
	global_store_dwordx4 v3, v[126:129], s[28:29] offset:1024
	global_store_dwordx4 v3, v[130:133], s[28:29] offset:2048
	global_store_dwordx4 v3, v[134:137], s[28:29] offset:3072
	v_mov_b32_e32 v9, 0
	v_mul_f32_e32 v174, v106, v106
	v_fmac_f32_e32 v174, v107, v107
	v_mul_f32_e32 v175, v108, v108
	v_fmac_f32_e32 v175, v109, v109
	v_add_f32_e32 v174, v174, v175
	v_add_f32_e32 v9, v9, v174
	v_mul_f32_e32 v174, v110, v110
	v_fmac_f32_e32 v174, v111, v111
	v_mul_f32_e32 v175, v112, v112
	v_fmac_f32_e32 v175, v113, v113
	v_add_f32_e32 v174, v174, v175
	v_add_f32_e32 v9, v9, v174
	v_mul_f32_e32 v174, v114, v114
	v_fmac_f32_e32 v174, v115, v115
	v_mul_f32_e32 v175, v116, v116
	v_fmac_f32_e32 v175, v117, v117
	v_add_f32_e32 v174, v174, v175
	v_add_f32_e32 v9, v9, v174
	v_mul_f32_e32 v174, v118, v118
	v_fmac_f32_e32 v174, v119, v119
	v_mul_f32_e32 v175, v120, v120
	v_fmac_f32_e32 v175, v121, v121
	v_add_f32_e32 v174, v174, v175
	v_add_f32_e32 v9, v9, v174
	v_mul_f32_e32 v174, v122, v122
	v_fmac_f32_e32 v174, v123, v123
	v_mul_f32_e32 v175, v124, v124
	v_fmac_f32_e32 v175, v125, v125
	v_add_f32_e32 v174, v174, v175
	v_add_f32_e32 v9, v9, v174
	v_mul_f32_e32 v174, v126, v126
	v_fmac_f32_e32 v174, v127, v127
	v_mul_f32_e32 v175, v128, v128
	v_fmac_f32_e32 v175, v129, v129
	v_add_f32_e32 v174, v174, v175
	v_add_f32_e32 v9, v9, v174
	v_mul_f32_e32 v174, v130, v130
	v_fmac_f32_e32 v174, v131, v131
	v_mul_f32_e32 v175, v132, v132
	v_fmac_f32_e32 v175, v133, v133
	v_add_f32_e32 v174, v174, v175
	v_add_f32_e32 v9, v9, v174
	v_mul_f32_e32 v174, v134, v134
	v_fmac_f32_e32 v174, v135, v135
	v_mul_f32_e32 v175, v136, v136
	v_fmac_f32_e32 v175, v137, v137
	v_add_f32_e32 v174, v174, v175
	v_add_f32_e32 v9, v9, v174
	s_nop 1
	v_add_f32_dpp v9, v9, v9 quad_perm:[1,0,3,2] row_mask:0xf bank_mask:0xf
	s_nop 1
	v_add_f32_dpp v9, v9, v9 quad_perm:[2,3,0,1] row_mask:0xf bank_mask:0xf
	s_nop 1
	v_add_f32_dpp v9, v9, v9 row_half_mirror row_mask:0xf bank_mask:0xf
	s_nop 1
	v_add_f32_dpp v9, v9, v9 row_mirror row_mask:0xf bank_mask:0xf
	s_nop 1
	v_add_f32_dpp v9, v9, v9 row_bcast:15 row_mask:0xa bank_mask:0xf
	s_nop 1
	v_add_f32_dpp v9, v9, v9 row_bcast:31 row_mask:0xc bank_mask:0xf
	s_nop 1
	v_readlane_b32 s79, v9, 63
	s_nop 1
	v_mov_b32_e32 v174, s79
	v_fmamk_f32 v174, v174, 0x3a000000, v177
	v_rsq_f32_e32 v176, v174
	s_nop 0
; __device__ __forceinline__ unsigned cvt_pk_bf16(float lo, float hi) { unsigned r; asm volatile("v_cvt_pk_bf16_f32 %0, %1, %2" : "=v"(r) : "v"(lo), "v"(hi)); return r; }
; __global__ void __launch_bounds__(512, 2) mega_fwd(Args a) {
;     ...
;       const float r2 = rsqrtf(wave_sum(ss2) * (1.f / DM) + EPS);
; #pragma unroll
;       for (int j = 0; j < 8; ++j) { const f32x4 gn = *(const f32x4*)(g2 + 4 * (64 * j + lane)); const f32x4 y = v[j] * r2 * gn;
;         u32x2 w; w.x = cvt_pk_bf16(y.x, y.y); w.y = cvt_pk_bf16(y.z, y.w); *(u32x2*)(XN + (size_t)m * DM + 4 * (64 * j + lane)) = w; }
;     }
	v_mul_f32_e32 v5, v106, v176
	v_mul_f32_e32 v6, v107, v176
	v_mul_f32_e32 v7, v108, v176
	v_mul_f32_e32 v8, v109, v176
	v_mul_f32_e32 v5, v5, v42
	v_mul_f32_e32 v6, v6, v43
	v_mul_f32_e32 v7, v7, v44
	v_mul_f32_e32 v8, v8, v45
	v_cvt_pk_bf16_f32 v154, v5, v6
	v_cvt_pk_bf16_f32 v155, v7, v8
	v_mul_f32_e32 v5, v110, v176
	v_mul_f32_e32 v6, v111, v176
	v_mul_f32_e32 v7, v112, v176
	v_mul_f32_e32 v8, v113, v176
	v_mul_f32_e32 v5, v5, v46
	v_mul_f32_e32 v6, v6, v47
	v_mul_f32_e32 v7, v7, v48
	v_mul_f32_e32 v8, v8, v49
	v_cvt_pk_bf16_f32 v156, v5, v6
	v_cvt_pk_bf16_f32 v157, v7, v8
	v_mul_f32_e32 v5, v114, v176
	v_mul_f32_e32 v6, v115, v176
	v_mul_f32_e32 v7, v116, v176
	v_mul_f32_e32 v8, v117, v176
	v_mul_f32_e32 v5, v5, v50
	v_mul_f32_e32 v6, v6, v51
	v_mul_f32_e32 v7, v7, v52
	v_mul_f32_e32 v8, v8, v53
	v_cvt_pk_bf16_f32 v158, v5, v6
	v_cvt_pk_bf16_f32 v159, v7, v8
	v_mul_f32_e32 v5, v118, v176
	v_mul_f32_e32 v6, v119, v176
	v_mul_f32_e32 v7, v120, v176
	v_mul_f32_e32 v8, v121, v176
	v_mul_f32_e32 v5, v5, v54
	v_mul_f32_e32 v6, v6, v55
	v_mul_f32_e32 v7, v7, v56
	v_mul_f32_e32 v8, v8, v57
	v_cvt_pk_bf16_f32 v160, v5, v6
	v_cvt_pk_bf16_f32 v161, v7, v8
	v_mul_f32_e32 v5, v122, v176
	v_mul_f32_e32 v6, v123, v176
	v_mul_f32_e32 v7, v124, v176
	v_mul_f32_e32 v8, v125, v176
	v_mul_f32_e32 v5, v5, v58
	v_mul_f32_e32 v6, v6, v59
	v_mul_f32_e32 v7, v7, v60
	v_mul_f32_e32 v8, v8, v61
	v_cvt_pk_bf16_f32 v162, v5, v6
	v_cvt_pk_bf16_f32 v163, v7, v8
	v_mul_f32_e32 v5, v126, v176
	v_mul_f32_e32 v6, v127, v176
	v_mul_f32_e32 v7, v128, v176
	v_mul_f32_e32 v8, v129, v176
	v_mul_f32_e32 v5, v5, v62
	v_mul_f32_e32 v6, v6, v63
	v_mul_f32_e32 v7, v7, v64
	v_mul_f32_e32 v8, v8, v65
	v_cvt_pk_bf16_f32 v166, v5, v6
	v_cvt_pk_bf16_f32 v167, v7, v8
	v_mul_f32_e32 v5, v130, v176
	v_mul_f32_e32 v6, v131, v176
	v_mul_f32_e32 v7, v132, v176
	v_mul_f32_e32 v8, v133, v176
	v_mul_f32_e32 v5, v5, v66
	v_mul_f32_e32 v6, v6, v67
	v_mul_f32_e32 v7, v7, v68
	v_mul_f32_e32 v8, v8, v69
	v_cvt_pk_bf16_f32 v168, v5, v6
	v_cvt_pk_bf16_f32 v169, v7, v8
	v_mul_f32_e32 v5, v134, v176
	v_mul_f32_e32 v6, v135, v176
	v_mul_f32_e32 v7, v136, v176
	v_mul_f32_e32 v8, v137, v176
	v_mul_f32_e32 v5, v5, v70
	v_mul_f32_e32 v6, v6, v71
	v_mul_f32_e32 v7, v7, v72
	v_mul_f32_e32 v8, v8, v73
	v_cvt_pk_bf16_f32 v172, v5, v6
	v_cvt_pk_bf16_f32 v173, v7, v8
	s_lshl_b32 s97, s19, 12
	s_add_u32 s30, s14, s97
	s_addc_u32 s31, s15, 0
	global_store_dwordx2 v4, v[154:155], s[30:31] offset:0
	global_store_dwordx2 v4, v[156:157], s[30:31] offset:512
	global_store_dwordx2 v4, v[158:159], s[30:31] offset:1024
	global_store_dwordx2 v4, v[160:161], s[30:31] offset:1536
	global_store_dwordx2 v4, v[162:163], s[30:31] offset:2048
	global_store_dwordx2 v4, v[166:167], s[30:31] offset:2560
	global_store_dwordx2 v4, v[168:169], s[30:31] offset:3072
	global_store_dwordx2 v4, v[172:173], s[30:31] offset:3584
	s_add_u32 s18, s19, s78
	s_branch .Lew5_loop
.Lew5_single:
	s_waitcnt vmcnt(0)
	v_mov_b32_e32 v9, 0
	v_lshlrev_b32_e32 v5, 16, v138
	v_and_b32_e32 v6, 0xffff0000, v138
	v_lshlrev_b32_e32 v7, 16, v139
	v_and_b32_e32 v8, 0xffff0000, v139
	v_mul_f32_e32 v174, v5, v5
	v_fmac_f32_e32 v174, v6, v6
	v_mul_f32_e32 v175, v7, v7
	v_fmac_f32_e32 v175, v8, v8
	v_add_f32_e32 v174, v174, v175
	v_add_f32_e32 v9, v9, v174
	v_lshlrev_b32_e32 v5, 16, v140
	v_and_b32_e32 v6, 0xffff0000, v140
	v_lshlrev_b32_e32 v7, 16, v141
	v_and_b32_e32 v8, 0xffff0000, v141
	v_mul_f32_e32 v174, v5, v5
	v_fmac_f32_e32 v174, v6, v6
	v_mul_f32_e32 v175, v7, v7
	v_fmac_f32_e32 v175, v8, v8
	v_add_f32_e32 v174, v174, v175
	v_add_f32_e32 v9, v9, v174
	v_lshlrev_b32_e32 v5, 16, v142
	v_and_b32_e32 v6, 0xffff0000, v142
	v_lshlrev_b32_e32 v7, 16, v143
	v_and_b32_e32 v8, 0xffff0000, v143
	v_mul_f32_e32 v174, v5, v5
	v_fmac_f32_e32 v174, v6, v6
	v_mul_f32_e32 v175, v7, v7
	v_fmac_f32_e32 v175, v8, v8
	v_add_f32_e32 v174, v174, v175
	v_add_f32_e32 v9, v9, v174
	v_lshlrev_b32_e32 v5, 16, v144
	v_and_b32_e32 v6, 0xffff0000, v144
	v_lshlrev_b32_e32 v7, 16, v145
	v_and_b32_e32 v8, 0xffff0000, v145
	v_mul_f32_e32 v174, v5, v5
	v_fmac_f32_e32 v174, v6, v6
	v_mul_f32_e32 v175, v7, v7
	v_fmac_f32_e32 v175, v8, v8
	v_add_f32_e32 v174, v174, v175
	v_add_f32_e32 v9, v9, v174
	v_lshlrev_b32_e32 v5, 16, v146
	v_and_b32_e32 v6, 0xffff0000, v146
	v_lshlrev_b32_e32 v7, 16, v147
	v_and_b32_e32 v8, 0xffff0000, v147
	v_mul_f32_e32 v174, v5, v5
	v_fmac_f32_e32 v174, v6, v6
	v_mul_f32_e32 v175, v7, v7
	v_fmac_f32_e32 v175, v8, v8
	v_add_f32_e32 v174, v174, v175
	v_add_f32_e32 v9, v9, v174
	v_lshlrev_b32_e32 v5, 16, v148
	v_and_b32_e32 v6, 0xffff0000, v148
	v_lshlrev_b32_e32 v7, 16, v149
	v_and_b32_e32 v8, 0xffff0000, v149
	v_mul_f32_e32 v174, v5, v5
	v_fmac_f32_e32 v174, v6, v6
	v_mul_f32_e32 v175, v7, v7
	v_fmac_f32_e32 v175, v8, v8
	v_add_f32_e32 v174, v174, v175
	v_add_f32_e32 v9, v9, v174
	v_lshlrev_b32_e32 v5, 16, v150
	v_and_b32_e32 v6, 0xffff0000, v150
	v_lshlrev_b32_e32 v7, 16, v151
	v_and_b32_e32 v8, 0xffff0000, v151
	v_mul_f32_e32 v174, v5, v5
	v_fmac_f32_e32 v174, v6, v6
	v_mul_f32_e32 v175, v7, v7
	v_fmac_f32_e32 v175, v8, v8
	v_add_f32_e32 v174, v174, v175
	v_add_f32_e32 v9, v9, v174
	v_lshlrev_b32_e32 v5, 16, v152
	v_and_b32_e32 v6, 0xffff0000, v152
	v_lshlrev_b32_e32 v7, 16, v153
	v_and_b32_e32 v8, 0xffff0000, v153
	v_mul_f32_e32 v174, v5, v5
	v_fmac_f32_e32 v174, v6, v6
	v_mul_f32_e32 v175, v7, v7
	v_fmac_f32_e32 v175, v8, v8
	v_add_f32_e32 v174, v174, v175
	v_add_f32_e32 v9, v9, v174
	s_nop 1
	v_add_f32_dpp v9, v9, v9 quad_perm:[1,0,3,2] row_mask:0xf bank_mask:0xf
	s_nop 1
	v_add_f32_dpp v9, v9, v9 quad_perm:[2,3,0,1] row_mask:0xf bank_mask:0xf
	s_nop 1
; __global__ void __launch_bounds__(512, 2) mega_fwd(Args a) {
;     ...
;       const float r = rsqrtf(wave_sum(ss) * (1.f / DM) + EPS); float ss2 = 0.f;
; #pragma unroll
;       for (int j = 0; j < 8; ++j) { const f32x4 gn = *(const f32x4*)(g1 + 4 * (64 * j + lane)); const f32x4 xv = xin[j];
;         v[j] = xv + v[j] * r * gn; *(f32x4*)(out + O_Y + (size_t)m * DM + 4 * (64 * j + lane)) = v[j];
;         ss2 += (v[j].x * v[j].x + v[j].y * v[j].y) + (v[j].z * v[j].z + v[j].w * v[j].w); }
;       const float r2 = rsqrtf(wave_sum(ss2) * (1.f / DM) + EPS);
	v_add_f32_dpp v9, v9, v9 row_half_mirror row_mask:0xf bank_mask:0xf
	s_nop 1
	v_add_f32_dpp v9, v9, v9 row_mirror row_mask:0xf bank_mask:0xf
	s_nop 1
	v_add_f32_dpp v9, v9, v9 row_bcast:15 row_mask:0xa bank_mask:0xf
	s_nop 1
	v_add_f32_dpp v9, v9, v9 row_bcast:31 row_mask:0xc bank_mask:0xf
	s_nop 1
	v_readlane_b32 s79, v9, 63
	s_nop 1
	v_mov_b32_e32 v174, s79
	v_fmamk_f32 v174, v174, 0x3a000000, v177
	v_rsq_f32_e32 v176, v174
	s_nop 0
	v_lshlrev_b32_e32 v5, 16, v138
	v_and_b32_e32 v6, 0xffff0000, v138
	v_lshlrev_b32_e32 v7, 16, v139
	v_and_b32_e32 v8, 0xffff0000, v139
	v_mul_f32_e32 v5, v5, v176
	v_mul_f32_e32 v6, v6, v176
	v_mul_f32_e32 v7, v7, v176
	v_mul_f32_e32 v8, v8, v176
	v_fmac_f32_e32 v74, v5, v10
	v_fmac_f32_e32 v75, v6, v11
	v_fmac_f32_e32 v76, v7, v12
	v_fmac_f32_e32 v77, v8, v13
	v_lshlrev_b32_e32 v5, 16, v140
	v_and_b32_e32 v6, 0xffff0000, v140
	v_lshlrev_b32_e32 v7, 16, v141
	v_and_b32_e32 v8, 0xffff0000, v141
	v_mul_f32_e32 v5, v5, v176
	v_mul_f32_e32 v6, v6, v176
	v_mul_f32_e32 v7, v7, v176
	v_mul_f32_e32 v8, v8, v176
	v_fmac_f32_e32 v78, v5, v14
	v_fmac_f32_e32 v79, v6, v15
	v_fmac_f32_e32 v80, v7, v16
	v_fmac_f32_e32 v81, v8, v17
	v_lshlrev_b32_e32 v5, 16, v142
	v_and_b32_e32 v6, 0xffff0000, v142
	v_lshlrev_b32_e32 v7, 16, v143
	v_and_b32_e32 v8, 0xffff0000, v143
	v_mul_f32_e32 v5, v5, v176
	v_mul_f32_e32 v6, v6, v176
	v_mul_f32_e32 v7, v7, v176
	v_mul_f32_e32 v8, v8, v176
	v_fmac_f32_e32 v82, v5, v18
	v_fmac_f32_e32 v83, v6, v19
	v_fmac_f32_e32 v84, v7, v20
	v_fmac_f32_e32 v85, v8, v21
	v_lshlrev_b32_e32 v5, 16, v144
	v_and_b32_e32 v6, 0xffff0000, v144
	v_lshlrev_b32_e32 v7, 16, v145
	v_and_b32_e32 v8, 0xffff0000, v145
	v_mul_f32_e32 v5, v5, v176
	v_mul_f32_e32 v6, v6, v176
	v_mul_f32_e32 v7, v7, v176
	v_mul_f32_e32 v8, v8, v176
	v_fmac_f32_e32 v86, v5, v22
	v_fmac_f32_e32 v87, v6, v23
	v_fmac_f32_e32 v88, v7, v24
	v_fmac_f32_e32 v89, v8, v25
	v_lshlrev_b32_e32 v5, 16, v146
	v_and_b32_e32 v6, 0xffff0000, v146
	v_lshlrev_b32_e32 v7, 16, v147
	v_and_b32_e32 v8, 0xffff0000, v147
	v_mul_f32_e32 v5, v5, v176
	v_mul_f32_e32 v6, v6, v176
	v_mul_f32_e32 v7, v7, v176
	v_mul_f32_e32 v8, v8, v176
	v_fmac_f32_e32 v90, v5, v26
	v_fmac_f32_e32 v91, v6, v27
	v_fmac_f32_e32 v92, v7, v28
	v_fmac_f32_e32 v93, v8, v29
	v_lshlrev_b32_e32 v5, 16, v148
	v_and_b32_e32 v6, 0xffff0000, v148
	v_lshlrev_b32_e32 v7, 16, v149
	v_and_b32_e32 v8, 0xffff0000, v149
	v_mul_f32_e32 v5, v5, v176
	v_mul_f32_e32 v6, v6, v176
	v_mul_f32_e32 v7, v7, v176
	v_mul_f32_e32 v8, v8, v176
	v_fmac_f32_e32 v94, v5, v30
	v_fmac_f32_e32 v95, v6, v31
	v_fmac_f32_e32 v96, v7, v32
	v_fmac_f32_e32 v97, v8, v33
	v_lshlrev_b32_e32 v5, 16, v150
	v_and_b32_e32 v6, 0xffff0000, v150
	v_lshlrev_b32_e32 v7, 16, v151
	v_and_b32_e32 v8, 0xffff0000, v151
	v_mul_f32_e32 v5, v5, v176
	v_mul_f32_e32 v6, v6, v176
	v_mul_f32_e32 v7, v7, v176
	v_mul_f32_e32 v8, v8, v176
	v_fmac_f32_e32 v98, v5, v34
	v_fmac_f32_e32 v99, v6, v35
	v_fmac_f32_e32 v100, v7, v36
	v_fmac_f32_e32 v101, v8, v37
	v_lshlrev_b32_e32 v5, 16, v152
	v_and_b32_e32 v6, 0xffff0000, v152
	v_lshlrev_b32_e32 v7, 16, v153
	v_and_b32_e32 v8, 0xffff0000, v153
	v_mul_f32_e32 v5, v5, v176
	v_mul_f32_e32 v6, v6, v176
	v_mul_f32_e32 v7, v7, v176
	v_mul_f32_e32 v8, v8, v176
	v_fmac_f32_e32 v102, v5, v38
	v_fmac_f32_e32 v103, v6, v39
	v_fmac_f32_e32 v104, v7, v40
	v_fmac_f32_e32 v105, v8, v41
	s_lshl_b32 s97, s18, 13
	s_add_u32 s24, s8, s97
	s_addc_u32 s25, s9, 0
	global_store_dwordx4 v2, v[74:77], s[24:25] offset:0
	global_store_dwordx4 v2, v[78:81], s[24:25] offset:1024
	global_store_dwordx4 v2, v[82:85], s[24:25] offset:2048
	global_store_dwordx4 v2, v[86:89], s[24:25] offset:3072
	global_store_dwordx4 v3, v[90:93], s[24:25] offset:0
	global_store_dwordx4 v3, v[94:97], s[24:25] offset:1024
	global_store_dwordx4 v3, v[98:101], s[24:25] offset:2048
	global_store_dwordx4 v3, v[102:105], s[24:25] offset:3072
	v_mov_b32_e32 v9, 0
	v_mul_f32_e32 v174, v74, v74
	v_fmac_f32_e32 v174, v75, v75
	v_mul_f32_e32 v175, v76, v76
	v_fmac_f32_e32 v175, v77, v77
	v_add_f32_e32 v174, v174, v175
	v_add_f32_e32 v9, v9, v174
	v_mul_f32_e32 v174, v78, v78
	v_fmac_f32_e32 v174, v79, v79
	v_mul_f32_e32 v175, v80, v80
	v_fmac_f32_e32 v175, v81, v81
	v_add_f32_e32 v174, v174, v175
	v_add_f32_e32 v9, v9, v174
	v_mul_f32_e32 v174, v82, v82
	v_fmac_f32_e32 v174, v83, v83
	v_mul_f32_e32 v175, v84, v84
	v_fmac_f32_e32 v175, v85, v85
	v_add_f32_e32 v174, v174, v175
	v_add_f32_e32 v9, v9, v174
	v_mul_f32_e32 v174, v86, v86
	v_fmac_f32_e32 v174, v87, v87
	v_mul_f32_e32 v175, v88, v88
	v_fmac_f32_e32 v175, v89, v89
	v_add_f32_e32 v174, v174, v175
	v_add_f32_e32 v9, v9, v174
	v_mul_f32_e32 v174, v90, v90
	v_fmac_f32_e32 v174, v91, v91
	v_mul_f32_e32 v175, v92, v92
	v_fmac_f32_e32 v175, v93, v93
	v_add_f32_e32 v174, v174, v175
	v_add_f32_e32 v9, v9, v174
	v_mul_f32_e32 v174, v94, v94
	v_fmac_f32_e32 v174, v95, v95
	v_mul_f32_e32 v175, v96, v96
	v_fmac_f32_e32 v175, v97, v97
	v_add_f32_e32 v174, v174, v175
	v_add_f32_e32 v9, v9, v174
	v_mul_f32_e32 v174, v98, v98
	v_fmac_f32_e32 v174, v99, v99
	v_mul_f32_e32 v175, v100, v100
	v_fmac_f32_e32 v175, v101, v101
	v_add_f32_e32 v174, v174, v175
	v_add_f32_e32 v9, v9, v174
	v_mul_f32_e32 v174, v102, v102
	v_fmac_f32_e32 v174, v103, v103
	v_mul_f32_e32 v175, v104, v104
	v_fmac_f32_e32 v175, v105, v105
; __device__ __forceinline__ unsigned cvt_pk_bf16(float lo, float hi) { unsigned r; asm volatile("v_cvt_pk_bf16_f32 %0, %1, %2" : "=v"(r) : "v"(lo), "v"(hi)); return r; }
; __global__ void __launch_bounds__(512, 2) mega_fwd(Args a) {
;     ...
;       const float r2 = rsqrtf(wave_sum(ss2) * (1.f / DM) + EPS);
; #pragma unroll
;       for (int j = 0; j < 8; ++j) { const f32x4 gn = *(const f32x4*)(g2 + 4 * (64 * j + lane)); const f32x4 y = v[j] * r2 * gn;
;         u32x2 w; w.x = cvt_pk_bf16(y.x, y.y); w.y = cvt_pk_bf16(y.z, y.w); *(u32x2*)(XN + (size_t)m * DM + 4 * (64 * j + lane)) = w; }
;     }
	v_add_f32_e32 v174, v174, v175
	v_add_f32_e32 v9, v9, v174
	s_nop 1
	v_add_f32_dpp v9, v9, v9 quad_perm:[1,0,3,2] row_mask:0xf bank_mask:0xf
	s_nop 1
	v_add_f32_dpp v9, v9, v9 quad_perm:[2,3,0,1] row_mask:0xf bank_mask:0xf
	s_nop 1
	v_add_f32_dpp v9, v9, v9 row_half_mirror row_mask:0xf bank_mask:0xf
	s_nop 1
	v_add_f32_dpp v9, v9, v9 row_mirror row_mask:0xf bank_mask:0xf
	s_nop 1
	v_add_f32_dpp v9, v9, v9 row_bcast:15 row_mask:0xa bank_mask:0xf
	s_nop 1
	v_add_f32_dpp v9, v9, v9 row_bcast:31 row_mask:0xc bank_mask:0xf
	s_nop 1
	v_readlane_b32 s79, v9, 63
	s_nop 1
	v_mov_b32_e32 v174, s79
	v_fmamk_f32 v174, v174, 0x3a000000, v177
	v_rsq_f32_e32 v176, v174
	s_nop 0
	v_mul_f32_e32 v5, v74, v176
	v_mul_f32_e32 v6, v75, v176
	v_mul_f32_e32 v7, v76, v176
	v_mul_f32_e32 v8, v77, v176
	v_mul_f32_e32 v5, v5, v42
	v_mul_f32_e32 v6, v6, v43
	v_mul_f32_e32 v7, v7, v44
	v_mul_f32_e32 v8, v8, v45
	v_cvt_pk_bf16_f32 v138, v5, v6
	v_cvt_pk_bf16_f32 v139, v7, v8
	v_mul_f32_e32 v5, v78, v176
	v_mul_f32_e32 v6, v79, v176
	v_mul_f32_e32 v7, v80, v176
	v_mul_f32_e32 v8, v81, v176
	v_mul_f32_e32 v5, v5, v46
	v_mul_f32_e32 v6, v6, v47
	v_mul_f32_e32 v7, v7, v48
	v_mul_f32_e32 v8, v8, v49
	v_cvt_pk_bf16_f32 v140, v5, v6
	v_cvt_pk_bf16_f32 v141, v7, v8
	v_mul_f32_e32 v5, v82, v176
	v_mul_f32_e32 v6, v83, v176
	v_mul_f32_e32 v7, v84, v176
	v_mul_f32_e32 v8, v85, v176
	v_mul_f32_e32 v5, v5, v50
	v_mul_f32_e32 v6, v6, v51
	v_mul_f32_e32 v7, v7, v52
	v_mul_f32_e32 v8, v8, v53
	v_cvt_pk_bf16_f32 v142, v5, v6
	v_cvt_pk_bf16_f32 v143, v7, v8
	v_mul_f32_e32 v5, v86, v176
	v_mul_f32_e32 v6, v87, v176
	v_mul_f32_e32 v7, v88, v176
	v_mul_f32_e32 v8, v89, v176
	v_mul_f32_e32 v5, v5, v54
	v_mul_f32_e32 v6, v6, v55
	v_mul_f32_e32 v7, v7, v56
	v_mul_f32_e32 v8, v8, v57
	v_cvt_pk_bf16_f32 v144, v5, v6
	v_cvt_pk_bf16_f32 v145, v7, v8
	v_mul_f32_e32 v5, v90, v176
	v_mul_f32_e32 v6, v91, v176
	v_mul_f32_e32 v7, v92, v176
	v_mul_f32_e32 v8, v93, v176
	v_mul_f32_e32 v5, v5, v58
	v_mul_f32_e32 v6, v6, v59
	v_mul_f32_e32 v7, v7, v60
	v_mul_f32_e32 v8, v8, v61
	v_cvt_pk_bf16_f32 v146, v5, v6
	v_cvt_pk_bf16_f32 v147, v7, v8
	v_mul_f32_e32 v5, v94, v176
	v_mul_f32_e32 v6, v95, v176
	v_mul_f32_e32 v7, v96, v176
	v_mul_f32_e32 v8, v97, v176
	v_mul_f32_e32 v5, v5, v62
	v_mul_f32_e32 v6, v6, v63
	v_mul_f32_e32 v7, v7, v64
	v_mul_f32_e32 v8, v8, v65
	v_cvt_pk_bf16_f32 v148, v5, v6
	v_cvt_pk_bf16_f32 v149, v7, v8
	v_mul_f32_e32 v5, v98, v176
	v_mul_f32_e32 v6, v99, v176
	v_mul_f32_e32 v7, v100, v176
	v_mul_f32_e32 v8, v101, v176
	v_mul_f32_e32 v5, v5, v66
	v_mul_f32_e32 v6, v6, v67
	v_mul_f32_e32 v7, v7, v68
	v_mul_f32_e32 v8, v8, v69
	v_cvt_pk_bf16_f32 v150, v5, v6
	v_cvt_pk_bf16_f32 v151, v7, v8
	v_mul_f32_e32 v5, v102, v176
	v_mul_f32_e32 v6, v103, v176
	v_mul_f32_e32 v7, v104, v176
	v_mul_f32_e32 v8, v105, v176
	v_mul_f32_e32 v5, v5, v70
	v_mul_f32_e32 v6, v6, v71
	v_mul_f32_e32 v7, v7, v72
	v_mul_f32_e32 v8, v8, v73
	v_cvt_pk_bf16_f32 v152, v5, v6
	v_cvt_pk_bf16_f32 v153, v7, v8
	s_lshl_b32 s97, s18, 12
	s_add_u32 s26, s14, s97
	s_addc_u32 s27, s15, 0
	global_store_dwordx2 v4, v[138:139], s[26:27] offset:0
	global_store_dwordx2 v4, v[140:141], s[26:27] offset:512
	global_store_dwordx2 v4, v[142:143], s[26:27] offset:1024
	global_store_dwordx2 v4, v[144:145], s[26:27] offset:1536
	global_store_dwordx2 v4, v[146:147], s[26:27] offset:2048
	global_store_dwordx2 v4, v[148:149], s[26:27] offset:2560
	global_store_dwordx2 v4, v[150:151], s[26:27] offset:3072
	global_store_dwordx2 v4, v[152:153], s[26:27] offset:3584
.Lew5_done:
.LBB0_1150:
	s_cmp_gt_i32 s87, 6
	s_cselect_b64 s[2:3], -1, 0
	s_and_b64 s[0:1], s[0:1], s[2:3]
	s_andn2_b64 vcc, exec, s[0:1]
	s_cbranch_vccnz .LBB0_1218
	s_cmp_gt_i32 s86, -1
	s_mov_b64 s[0:1], -1
	s_cbranch_scc0 .LBB0_1205
	s_waitcnt vmcnt(0)
	s_waitcnt vmcnt(0) lgkmcnt(0)
	s_barrier
	s_mov_b64 s[0:1], exec
	v_readlane_b32 s4, v251, 19
	v_readlane_b32 s5, v251, 20
	s_and_b64 s[4:5], s[0:1], s[4:5]
	s_mov_b64 exec, s[4:5]
	s_cbranch_execz .LBB0_1204
	s_add_i32 s4, 0, 0x25fa0
	v_mov_b32_e32 v2, s4
	s_waitcnt vmcnt(0) expcnt(0) lgkmcnt(0)
	ds_read_b32 v4, v2
	s_add_i32 s4, 0, 0x25fa4
	v_mov_b32_e32 v2, s4
	ds_read_b32 v2, v2
	s_waitcnt lgkmcnt(1)
	v_cmp_ne_u32_e32 vcc, 0, v4
	s_cbranch_vccnz .LBB0_1168
	v_readlane_b32 s4, v251, 0
	s_mul_i32 s12, s83, s4
	s_add_u32 s4, s84, 0x225c8200
	s_addc_u32 s5, s85, 0
	s_add_u32 s6, s84, 0x225c8400
	s_addc_u32 s7, s85, 0
	s_add_u32 s8, s84, 0x225c8500
	s_addc_u32 s9, s85, 0
	s_add_u32 s14, s84, 0x225c8600
	s_addc_u32 s15, s85, 0
	s_add_u32 s16, s84, 0x225c8700
	s_addc_u32 s17, s85, 0
	s_add_u32 s18, s84, 0x225c8800
	s_addc_u32 s19, s85, 0
	s_add_u32 s20, s84, 0x225c8900
	s_addc_u32 s21, s85, 0
	s_add_u32 s24, s84, 0x225c8a00
	s_addc_u32 s25, s85, 0
	s_add_u32 s28, s84, 0x225c8b00
	s_addc_u32 s29, s85, 0
	s_add_u32 s30, s84, 0x225c8c00
	s_addc_u32 s31, s85, 0
	s_add_u32 s34, s84, 0x225c8d00
	s_addc_u32 s35, s85, 0
	s_add_u32 s36, s84, 0x225c8e00
	s_addc_u32 s37, s85, 0
	s_add_u32 s38, s84, 0x225c8f00
	s_addc_u32 s39, s85, 0
	s_add_u32 s40, s84, 0x225c9000
	s_addc_u32 s41, s85, 0
	s_add_u32 s42, s84, 0x225c9100
	s_addc_u32 s43, s85, 0
	s_add_u32 s44, s84, 0x225c9200
	s_addc_u32 s45, s85, 0
	s_add_u32 s48, s84, 0x225c9300
	s_mul_i32 s12, s12, s82
	s_addc_u32 s49, s85, 0
	s_mov_b32 s13, 1
	v_mov_b32_e32 v18, 0
	s_branch .LBB0_1156
